# sample-row blocks: prefetch ss/x/gates before operand loads, 16x128 patches without K-split or barriers for the N=5632 phases, no trailing vmcnt(0)
# baseline (speedup 1.0000x reference)
.LBB0_175:
	s_or_b64 exec, exec, s[6:7]
	s_add_u32 s48, s38, 0x9e00000
	s_addc_u32 s49, s39, 0
	s_add_u32 s22, s38, 0x11f00000
	s_addc_u32 s23, s39, 0
	s_cmpk_lt_i32 s2, 0x1616
	v_mov_b32_e32 v0, v206
	s_cselect_b64 s[14:15], -1, 0
	v_mov_b32_e32 v9, v206
	s_barrier
	v_lshrrev_b32_e32 v11, 6, v206
	v_and_b32_e32 v8, 63, v206
	s_load_dwordx2 s[96:97], s[0:1], 0x118
	v_readfirstlane_b32 s86, v11
	v_and_b32_e32 v9, 15, v8
	v_lshrrev_b32_e32 v10, 4, v8
	s_mov_b32 s32, s86
	s_mov_b32 s101, 0
	s_mov_b32 s87, s2
	v_lshlrev_b32_e32 v11, 4, v10
	s_mul_i32 s100, s101, 0x400
	v_mov_b32_e32 v12, 0x800
	v_mul_u32_u24_e32 v12, v9, v12
	v_mov_b32_e32 v14, 0x800
	v_mul_u32_u24_e32 v14, v9, v14
	v_add_u32_e32 v12, v12, v11
	v_add_u32_e32 v14, v14, v11
	v_add_u32_e32 v12, s100, v12
	v_add_u32_e32 v14, s100, v14
	v_mov_b32_e32 v13, 0
	v_mov_b32_e32 v15, 0
	s_lshl_b32 s100, s32, 10
	s_add_u32 s100, s100, 0x20000
	v_lshlrev_b32_e32 v34, 4, v8
	v_add_u32_e32 v34, s100, v34
	s_lshl_b32 s100, s32, 8
	s_add_u32 s100, s100, 0x22000
	v_lshlrev_b32_e32 v35, 2, v8
	v_add_u32_e32 v35, s100, v35
	v_xor_b32_e32 v32, 16, v8
	v_lshlrev_b32_e32 v32, 2, v32
	v_xor_b32_e32 v33, 32, v8
	v_lshlrev_b32_e32 v33, 2, v33
	s_waitcnt lgkmcnt(0)
.Lsg_p1_loop:
	s_cmp_ge_u32 s87, 0x160
	s_cbranch_scc1 .Lsg_p1_done
	s_and_b32 s100, s87, 15
	s_lshl_b32 s100, s100, 4
	s_add_u32 s100, s100, 0x10000
	v_add_u32_e32 v24, s100, v9
	s_lshr_b32 s101, s87, 4
	s_lshl_b32 s101, s101, 7
	s_lshl_b32 vcc_lo, s32, 4
	s_add_u32 s101, s101, vcc_lo
	v_lshlrev_b32_e32 v25, 2, v10
	v_add_u32_e32 v25, s101, v25
	s_add_u32 s88, s96, 0x4100000
	s_addc_u32 s89, s97, 0
	v_lshlrev_b32_e32 v26, 6, v24
	v_lshl_add_u32 v26, v10, 4, v26
	global_load_dwordx4 v[28:31], v26, s[88:89]
	s_mul_i32 vcc_lo, s100, 0x800
	s_add_u32 s88, s96, vcc_lo
	s_addc_u32 s89, s97, 0
	s_add_u32 s88, s88, 0x9e00000
	s_addc_u32 s89, s89, 0
	s_lshr_b32 vcc_lo, s101, 7
	s_lshl_b32 vcc_lo, vcc_lo, 8
	s_and_b32 vcc_hi, s101, 0x7f
	s_add_u32 vcc_lo, vcc_lo, vcc_hi
	s_mul_i32 vcc_lo, vcc_lo, 0x800
	s_add_u32 s92, s96, vcc_lo
	s_addc_u32 s93, s97, 0
	s_add_u32 s92, s92, 0x100000
	s_addc_u32 s93, s93, 0
	v_lshl_add_u64 v[0:1], s[88:89], 0, v[12:13]
	v_lshl_add_u64 v[2:3], s[92:93], 0, v[14:15]
	s_mov_b32 vcc_lo, 0x40000
	s_mov_b32 vcc_hi, 0
	v_lshl_add_u64 v[4:5], v[2:3], 0, vcc
	v_mov_b32_e32 v16, 0
	v_mov_b32_e32 v17, 0
	v_mov_b32_e32 v18, 0
	v_mov_b32_e32 v19, 0
	v_mov_b32_e32 v20, 0
	v_mov_b32_e32 v21, 0
	v_mov_b32_e32 v22, 0
	v_mov_b32_e32 v23, 0
	global_load_dwordx4 v[40:43], v[0:1], off
	global_load_dwordx4 v[44:47], v[2:3], off
	global_load_dwordx4 v[48:51], v[4:5], off
	global_load_dwordx4 v[52:55], v[0:1], off offset:64
	global_load_dwordx4 v[56:59], v[2:3], off offset:64
	global_load_dwordx4 v[60:63], v[4:5], off offset:64
	global_load_dwordx4 v[64:67], v[0:1], off offset:128
	global_load_dwordx4 v[68:71], v[2:3], off offset:128
	global_load_dwordx4 v[72:75], v[4:5], off offset:128
	global_load_dwordx4 v[76:79], v[0:1], off offset:192
	global_load_dwordx4 v[80:83], v[2:3], off offset:192
	global_load_dwordx4 v[84:87], v[4:5], off offset:192
	global_load_dwordx4 v[88:91], v[0:1], off offset:256
	global_load_dwordx4 v[92:95], v[2:3], off offset:256
	global_load_dwordx4 v[96:99], v[4:5], off offset:256
	global_load_dwordx4 v[100:103], v[0:1], off offset:320
	global_load_dwordx4 v[104:107], v[2:3], off offset:320
	global_load_dwordx4 v[108:111], v[4:5], off offset:320
	global_load_dwordx4 v[112:115], v[0:1], off offset:384
	global_load_dwordx4 v[116:119], v[2:3], off offset:384
	global_load_dwordx4 v[120:123], v[4:5], off offset:384
	global_load_dwordx4 v[124:127], v[0:1], off offset:448
	global_load_dwordx4 v[128:131], v[2:3], off offset:448
	global_load_dwordx4 v[132:135], v[4:5], off offset:448
	global_load_dwordx4 v[136:139], v[0:1], off offset:512
	global_load_dwordx4 v[140:143], v[2:3], off offset:512
	global_load_dwordx4 v[144:147], v[4:5], off offset:512
	global_load_dwordx4 v[148:151], v[0:1], off offset:576
	global_load_dwordx4 v[152:155], v[2:3], off offset:576
	global_load_dwordx4 v[156:159], v[4:5], off offset:576
	global_load_dwordx4 v[160:163], v[0:1], off offset:640
	global_load_dwordx4 v[164:167], v[2:3], off offset:640
	global_load_dwordx4 v[168:171], v[4:5], off offset:640
	global_load_dwordx4 v[172:175], v[0:1], off offset:704
	global_load_dwordx4 v[176:179], v[2:3], off offset:704
	global_load_dwordx4 v[180:183], v[4:5], off offset:704
	global_load_dwordx4 v[184:187], v[0:1], off offset:768
	global_load_dwordx4 v[188:191], v[2:3], off offset:768
	global_load_dwordx4 v[192:195], v[4:5], off offset:768
	global_load_dwordx4 v[196:199], v[0:1], off offset:832
	global_load_dwordx4 v[200:203], v[2:3], off offset:832
	global_load_dwordx4 v[212:215], v[4:5], off offset:832
	global_load_dwordx4 v[216:219], v[0:1], off offset:896
	global_load_dwordx4 v[220:223], v[2:3], off offset:896
	global_load_dwordx4 v[224:227], v[4:5], off offset:896
	global_load_dwordx4 v[228:231], v[0:1], off offset:960
	global_load_dwordx4 v[232:235], v[2:3], off offset:960
	global_load_dwordx4 v[236:239], v[4:5], off offset:960
	s_waitcnt vmcnt(45)
	v_mfma_f32_16x16x32_bf16 v[16:19], v[44:47], v[40:43], v[16:19]
	v_mfma_f32_16x16x32_bf16 v[20:23], v[48:51], v[40:43], v[20:23]
	s_waitcnt vmcnt(42)
	v_mfma_f32_16x16x32_bf16 v[16:19], v[56:59], v[52:55], v[16:19]
	v_mfma_f32_16x16x32_bf16 v[20:23], v[60:63], v[52:55], v[20:23]
	s_waitcnt vmcnt(39)
	v_mfma_f32_16x16x32_bf16 v[16:19], v[68:71], v[64:67], v[16:19]
	v_mfma_f32_16x16x32_bf16 v[20:23], v[72:75], v[64:67], v[20:23]
	s_waitcnt vmcnt(36)
	v_mfma_f32_16x16x32_bf16 v[16:19], v[80:83], v[76:79], v[16:19]
	v_mfma_f32_16x16x32_bf16 v[20:23], v[84:87], v[76:79], v[20:23]
	s_waitcnt vmcnt(33)
	v_mfma_f32_16x16x32_bf16 v[16:19], v[92:95], v[88:91], v[16:19]
	v_mfma_f32_16x16x32_bf16 v[20:23], v[96:99], v[88:91], v[20:23]
	s_waitcnt vmcnt(30)
	v_mfma_f32_16x16x32_bf16 v[16:19], v[104:107], v[100:103], v[16:19]
	v_mfma_f32_16x16x32_bf16 v[20:23], v[108:111], v[100:103], v[20:23]
	s_waitcnt vmcnt(27)
	v_mfma_f32_16x16x32_bf16 v[16:19], v[116:119], v[112:115], v[16:19]
	v_mfma_f32_16x16x32_bf16 v[20:23], v[120:123], v[112:115], v[20:23]
	s_waitcnt vmcnt(24)
	v_mfma_f32_16x16x32_bf16 v[16:19], v[128:131], v[124:127], v[16:19]
	v_mfma_f32_16x16x32_bf16 v[20:23], v[132:135], v[124:127], v[20:23]
	global_load_dwordx4 v[40:43], v[0:1], off offset:1024
	global_load_dwordx4 v[44:47], v[2:3], off offset:1024
	global_load_dwordx4 v[48:51], v[4:5], off offset:1024
	global_load_dwordx4 v[52:55], v[0:1], off offset:1088
	global_load_dwordx4 v[56:59], v[2:3], off offset:1088
	global_load_dwordx4 v[60:63], v[4:5], off offset:1088
	global_load_dwordx4 v[64:67], v[0:1], off offset:1152
	global_load_dwordx4 v[68:71], v[2:3], off offset:1152
	global_load_dwordx4 v[72:75], v[4:5], off offset:1152
	global_load_dwordx4 v[76:79], v[0:1], off offset:1216
	global_load_dwordx4 v[80:83], v[2:3], off offset:1216
	global_load_dwordx4 v[84:87], v[4:5], off offset:1216
	global_load_dwordx4 v[88:91], v[0:1], off offset:1280
	global_load_dwordx4 v[92:95], v[2:3], off offset:1280
	global_load_dwordx4 v[96:99], v[4:5], off offset:1280
	global_load_dwordx4 v[100:103], v[0:1], off offset:1344
	global_load_dwordx4 v[104:107], v[2:3], off offset:1344
	global_load_dwordx4 v[108:111], v[4:5], off offset:1344
	global_load_dwordx4 v[112:115], v[0:1], off offset:1408
	global_load_dwordx4 v[116:119], v[2:3], off offset:1408
	global_load_dwordx4 v[120:123], v[4:5], off offset:1408
	global_load_dwordx4 v[124:127], v[0:1], off offset:1472
	global_load_dwordx4 v[128:131], v[2:3], off offset:1472
	global_load_dwordx4 v[132:135], v[4:5], off offset:1472
	s_waitcnt vmcnt(45)
	v_mfma_f32_16x16x32_bf16 v[16:19], v[140:143], v[136:139], v[16:19]
	v_mfma_f32_16x16x32_bf16 v[20:23], v[144:147], v[136:139], v[20:23]
	s_waitcnt vmcnt(42)
	v_mfma_f32_16x16x32_bf16 v[16:19], v[152:155], v[148:151], v[16:19]
	v_mfma_f32_16x16x32_bf16 v[20:23], v[156:159], v[148:151], v[20:23]
	s_waitcnt vmcnt(39)
	v_mfma_f32_16x16x32_bf16 v[16:19], v[164:167], v[160:163], v[16:19]
	v_mfma_f32_16x16x32_bf16 v[20:23], v[168:171], v[160:163], v[20:23]
	s_waitcnt vmcnt(36)
	v_mfma_f32_16x16x32_bf16 v[16:19], v[176:179], v[172:175], v[16:19]
	v_mfma_f32_16x16x32_bf16 v[20:23], v[180:183], v[172:175], v[20:23]
	s_waitcnt vmcnt(33)
	v_mfma_f32_16x16x32_bf16 v[16:19], v[188:191], v[184:187], v[16:19]
	v_mfma_f32_16x16x32_bf16 v[20:23], v[192:195], v[184:187], v[20:23]
	s_waitcnt vmcnt(30)
	v_mfma_f32_16x16x32_bf16 v[16:19], v[200:203], v[196:199], v[16:19]
	v_mfma_f32_16x16x32_bf16 v[20:23], v[212:215], v[196:199], v[20:23]
	s_waitcnt vmcnt(27)
	v_mfma_f32_16x16x32_bf16 v[16:19], v[220:223], v[216:219], v[16:19]
	v_mfma_f32_16x16x32_bf16 v[20:23], v[224:227], v[216:219], v[20:23]
	s_waitcnt vmcnt(24)
	v_mfma_f32_16x16x32_bf16 v[16:19], v[232:235], v[228:231], v[16:19]
	v_mfma_f32_16x16x32_bf16 v[20:23], v[236:239], v[228:231], v[20:23]
	global_load_dwordx4 v[136:139], v[0:1], off offset:1536
	global_load_dwordx4 v[140:143], v[2:3], off offset:1536
	global_load_dwordx4 v[144:147], v[4:5], off offset:1536
	global_load_dwordx4 v[148:151], v[0:1], off offset:1600
	global_load_dwordx4 v[152:155], v[2:3], off offset:1600
	global_load_dwordx4 v[156:159], v[4:5], off offset:1600
	global_load_dwordx4 v[160:163], v[0:1], off offset:1664
	global_load_dwordx4 v[164:167], v[2:3], off offset:1664
	global_load_dwordx4 v[168:171], v[4:5], off offset:1664
	global_load_dwordx4 v[172:175], v[0:1], off offset:1728
	global_load_dwordx4 v[176:179], v[2:3], off offset:1728
	global_load_dwordx4 v[180:183], v[4:5], off offset:1728
	global_load_dwordx4 v[184:187], v[0:1], off offset:1792
	global_load_dwordx4 v[188:191], v[2:3], off offset:1792
	global_load_dwordx4 v[192:195], v[4:5], off offset:1792
	global_load_dwordx4 v[196:199], v[0:1], off offset:1856
	global_load_dwordx4 v[200:203], v[2:3], off offset:1856
	global_load_dwordx4 v[212:215], v[4:5], off offset:1856
	global_load_dwordx4 v[216:219], v[0:1], off offset:1920
	global_load_dwordx4 v[220:223], v[2:3], off offset:1920
	global_load_dwordx4 v[224:227], v[4:5], off offset:1920
	global_load_dwordx4 v[228:231], v[0:1], off offset:1984
	global_load_dwordx4 v[232:235], v[2:3], off offset:1984
	global_load_dwordx4 v[236:239], v[4:5], off offset:1984
	s_waitcnt vmcnt(45)
	v_mfma_f32_16x16x32_bf16 v[16:19], v[44:47], v[40:43], v[16:19]
	v_mfma_f32_16x16x32_bf16 v[20:23], v[48:51], v[40:43], v[20:23]
	s_waitcnt vmcnt(42)
	v_mfma_f32_16x16x32_bf16 v[16:19], v[56:59], v[52:55], v[16:19]
	v_mfma_f32_16x16x32_bf16 v[20:23], v[60:63], v[52:55], v[20:23]
	s_waitcnt vmcnt(39)
	v_mfma_f32_16x16x32_bf16 v[16:19], v[68:71], v[64:67], v[16:19]
	v_mfma_f32_16x16x32_bf16 v[20:23], v[72:75], v[64:67], v[20:23]
	s_waitcnt vmcnt(36)
	v_mfma_f32_16x16x32_bf16 v[16:19], v[80:83], v[76:79], v[16:19]
	v_mfma_f32_16x16x32_bf16 v[20:23], v[84:87], v[76:79], v[20:23]
	s_waitcnt vmcnt(33)
	v_mfma_f32_16x16x32_bf16 v[16:19], v[92:95], v[88:91], v[16:19]
	v_mfma_f32_16x16x32_bf16 v[20:23], v[96:99], v[88:91], v[20:23]
	s_waitcnt vmcnt(30)
	v_mfma_f32_16x16x32_bf16 v[16:19], v[104:107], v[100:103], v[16:19]
	v_mfma_f32_16x16x32_bf16 v[20:23], v[108:111], v[100:103], v[20:23]
	s_waitcnt vmcnt(27)
	v_mfma_f32_16x16x32_bf16 v[16:19], v[116:119], v[112:115], v[16:19]
	v_mfma_f32_16x16x32_bf16 v[20:23], v[120:123], v[112:115], v[20:23]
	s_waitcnt vmcnt(24)
	v_mfma_f32_16x16x32_bf16 v[16:19], v[128:131], v[124:127], v[16:19]
	v_mfma_f32_16x16x32_bf16 v[20:23], v[132:135], v[124:127], v[20:23]
	s_waitcnt vmcnt(21)
	v_mfma_f32_16x16x32_bf16 v[16:19], v[140:143], v[136:139], v[16:19]
	v_mfma_f32_16x16x32_bf16 v[20:23], v[144:147], v[136:139], v[20:23]
	s_waitcnt vmcnt(18)
	v_mfma_f32_16x16x32_bf16 v[16:19], v[152:155], v[148:151], v[16:19]
	v_mfma_f32_16x16x32_bf16 v[20:23], v[156:159], v[148:151], v[20:23]
	s_waitcnt vmcnt(15)
	v_mfma_f32_16x16x32_bf16 v[16:19], v[164:167], v[160:163], v[16:19]
	v_mfma_f32_16x16x32_bf16 v[20:23], v[168:171], v[160:163], v[20:23]
	s_waitcnt vmcnt(12)
	v_mfma_f32_16x16x32_bf16 v[16:19], v[176:179], v[172:175], v[16:19]
	v_mfma_f32_16x16x32_bf16 v[20:23], v[180:183], v[172:175], v[20:23]
	s_waitcnt vmcnt(9)
	v_mfma_f32_16x16x32_bf16 v[16:19], v[188:191], v[184:187], v[16:19]
	v_mfma_f32_16x16x32_bf16 v[20:23], v[192:195], v[184:187], v[20:23]
	s_waitcnt vmcnt(6)
	v_mfma_f32_16x16x32_bf16 v[16:19], v[200:203], v[196:199], v[16:19]
	v_mfma_f32_16x16x32_bf16 v[20:23], v[212:215], v[196:199], v[20:23]
	s_waitcnt vmcnt(3)
	v_mfma_f32_16x16x32_bf16 v[16:19], v[220:223], v[216:219], v[16:19]
	v_mfma_f32_16x16x32_bf16 v[20:23], v[224:227], v[216:219], v[20:23]
	s_waitcnt vmcnt(0)
	v_mfma_f32_16x16x32_bf16 v[16:19], v[232:235], v[228:231], v[16:19]
	v_mfma_f32_16x16x32_bf16 v[20:23], v[236:239], v[228:231], v[20:23]
	s_nop 7
	s_nop 7
	v_add_f32_e32 v28, v28, v29
	v_add_f32_e32 v30, v30, v31
	v_add_f32_e32 v28, v28, v30
	s_nop 1
	ds_bpermute_b32 v29, v32, v28
	s_waitcnt lgkmcnt(0)
	v_add_f32_e32 v28, v28, v29
	s_nop 1
	ds_bpermute_b32 v29, v33, v28
	s_waitcnt lgkmcnt(0)
	v_add_f32_e32 v28, v28, v29
	v_mov_b32_e32 v29, 0x358637bd
	s_mov_b32 s101, 0x3a800000
	v_fma_f32 v28, v28, s101, v29
	v_rsq_f32_e32 v28, v28
	s_nop 1
	v_mul_f32_e32 v16, v16, v28
	v_mul_f32_e32 v20, v20, v28
	v_mul_f32_e32 v17, v17, v28
	v_mul_f32_e32 v21, v21, v28
	v_mul_f32_e32 v18, v18, v28
	v_mul_f32_e32 v22, v22, v28
	v_mul_f32_e32 v19, v19, v28
	v_mul_f32_e32 v23, v23, v28
	v_mul_f32_e32 v44, 0xbfb8aa3b, v16
	v_mul_f32_e32 v45, 0xbfb8aa3b, v17
	v_mul_f32_e32 v46, 0xbfb8aa3b, v18
	v_mul_f32_e32 v47, 0xbfb8aa3b, v19
	v_exp_f32_e32 v44, v44
	v_exp_f32_e32 v45, v45
	v_exp_f32_e32 v46, v46
	v_exp_f32_e32 v47, v47
	s_nop 1
	v_add_f32_e32 v44, 1.0, v44
	v_add_f32_e32 v45, 1.0, v45
	v_add_f32_e32 v46, 1.0, v46
	v_add_f32_e32 v47, 1.0, v47
	v_rcp_f32_e32 v44, v44
	v_rcp_f32_e32 v45, v45
	v_rcp_f32_e32 v46, v46
	v_rcp_f32_e32 v47, v47
	s_nop 1
	v_mul_f32_e32 v44, v16, v44
	v_mul_f32_e32 v44, v44, v20
	v_mul_f32_e32 v45, v17, v45
	v_mul_f32_e32 v45, v45, v21
	v_mul_f32_e32 v46, v18, v46
	v_mul_f32_e32 v46, v46, v22
	v_mul_f32_e32 v47, v19, v47
	v_mul_f32_e32 v47, v47, v23
	v_cvt_pk_bf16_f32 v40, v44, v45
	v_cvt_pk_bf16_f32 v41, v46, v47
	v_mov_b32_e32 v26, 0x1600
	v_mul_u32_u24_e32 v26, v24, v26
	v_lshl_add_u32 v26, v25, 1, v26
	s_add_u32 s92, s96, 0x11f00000
	s_addc_u32 s93, s97, 0
	global_store_dwordx2 v26, v[40:41], s[92:93]
.Lsg_p1_noepi:
	s_add_u32 s87, s87, s46
	s_branch .Lsg_p1_loop
.Lsg_p1_done:
	v_mov_b32_e32 v0, v206
	v_mov_b32_e32 v9, v206
	s_nop 1
	s_ashr_i32 s74, s46, 31
	s_ashr_i32 s3, s2, 31
	s_and_b64 vcc, exec, s[14:15]
	v_readfirstlane_b32 s7, v9
	s_cbranch_vccz .LBB0_195
	v_lshlrev_b32_e32 v0, 4, v9
	v_add_u32_e32 v1, 0x2000, v0
	v_ashrrev_i32_e32 v2, 31, v1
	v_lshrrev_b32_e32 v2, 22, v2
	v_add_u32_e32 v2, v1, v2
	v_ashrrev_i32_e32 v8, 10, v2
	v_mul_i32_i24_e32 v2, 0x400, v8
	v_sub_u32_e32 v1, v1, v2
	v_lshrrev_b32_e32 v2, 4, v1
	v_bitop3_b32 v1, v2, v1, 32 bitop3:0x6c
	v_ashrrev_i32_e32 v2, 31, v1
	v_lshrrev_b32_e32 v2, 26, v2
	v_add_u32_e32 v2, v1, v2
	v_lshlrev_b32_e32 v3, 3, v8
	v_ashrrev_i32_e32 v10, 6, v2
	v_and_b32_e32 v3, -16, v3
	v_add_u32_e32 v3, v10, v3
	v_and_b32_e32 v4, 3, v10
	s_mov_b32 s6, 0x1fffe0
	v_lshrrev_b32_e32 v5, 2, v3
	v_lshlrev_b32_e32 v6, 1, v3
	v_and_b32_e32 v2, 0xc0, v2
	v_and_or_b32 v4, v3, s6, v4
	v_and_b32_e32 v5, 4, v5
	v_and_b32_e32 v6, 24, v6
	v_sub_u32_e32 v1, v1, v2
	v_mov_b32_e32 v2, 1
	v_or3_b32 v4, v4, v5, v6
	v_lshlrev_b32_e32 v5, 5, v8
	v_ashrrev_i16_sdwa v1, v2, sext(v1) dst_sel:DWORD dst_unused:UNUSED_PAD src0_sel:DWORD src1_sel:BYTE_0
	v_and_b32_e32 v5, 32, v5
	v_bfe_i32 v11, v1, 0, 16
	v_add_lshl_u32 v1, v5, v11, 1
	v_lshl_add_u32 v128, v4, 11, v1
	v_lshl_add_u32 v130, v3, 11, v1
	v_bfe_i32 v1, v9, 27, 1
	v_lshrrev_b32_e32 v1, 22, v1
	v_add_u32_e32 v1, v0, v1
	v_and_b32_e32 v1, 0xfffffc00, v1
	v_sub_u32_e32 v0, v0, v1
	v_lshrrev_b32_e32 v1, 4, v0
	v_ashrrev_i32_e32 v3, 31, v9
	v_bitop3_b32 v0, v1, v0, 32 bitop3:0x6c
	v_lshrrev_b32_e32 v3, 26, v3
	v_ashrrev_i32_e32 v1, 31, v0
	v_add_u32_e32 v3, v9, v3
	v_lshrrev_b32_e32 v1, 26, v1
	v_ashrrev_i32_e32 v13, 6, v3
	v_add_u32_e32 v1, v0, v1
	v_lshlrev_b32_e32 v3, 3, v13
	v_ashrrev_i32_e32 v12, 6, v1
	v_and_b32_e32 v3, -16, v3
	s_add_u32 s35, s38, 0x100000
	v_add_u32_e32 v3, v12, v3
	v_and_b32_e32 v4, 3, v12
	s_addc_u32 s50, s39, 0
	v_and_or_b32 v4, v3, s6, v4
	s_lshr_b32 s6, s3, 29
	s_add_i32 s6, s2, s6
	s_and_b32 s8, s6, -8
	s_sub_i32 s8, s2, s8
	s_ashr_i32 s10, s7, 6
	s_mul_i32 s11, s8, 0x2c0
	s_ashr_i32 s16, s7, 8
	s_lshl_b32 s51, s10, 10
	s_add_i32 s11, s11, 0
	s_ashr_i32 s6, s6, 3
	s_mul_i32 s9, s8, 0x2c0
	s_cmp_lt_i32 s8, 6
	s_cselect_b32 s8, s9, s11
	s_add_i32 s8, s8, s6
	s_mul_hi_i32 s6, s8, 0x2e8ba2e9
	s_lshr_b32 s9, s6, 31
	s_ashr_i32 s6, s6, 4
	v_lshrrev_b32_e32 v5, 2, v3
	v_lshlrev_b32_e32 v6, 1, v3
	v_and_b32_e32 v1, 0xc0, v1
	s_add_i32 s6, s6, s9
	v_and_b32_e32 v5, 4, v5
	v_and_b32_e32 v6, 24, v6
	v_sub_u32_e32 v0, v0, v1
	s_lshl_b32 s11, s6, 2
	v_or3_b32 v4, v4, v5, v6
	v_lshlrev_b32_e32 v5, 5, v13
	v_ashrrev_i16_sdwa v0, v2, sext(v0) dst_sel:DWORD dst_unused:UNUSED_PAD src0_sel:DWORD src1_sel:BYTE_0
	s_sub_i32 s9, 0x100, s11
	s_mulk_i32 s6, 0x58
	v_and_b32_e32 v5, 32, v5
	v_bfe_i32 v14, v0, 0, 16
	s_min_u32 s12, s9, 4
	s_sub_i32 s13, s8, s6
	v_add_lshl_u32 v0, v5, v14, 1
	s_sext_i32_i8 s6, s13
	v_cvt_f32_ubyte0_e32 v2, s12
	v_lshl_add_u32 v132, v4, 11, v0
	v_cvt_f32_i32_e32 v1, s6
	v_rcp_iflag_f32_e32 v4, v2
	v_lshl_add_u32 v134, v3, 11, v0
	s_ashr_i32 s6, s6, 30
	s_or_b32 s6, s6, 1
	v_mul_f32_e32 v0, v1, v4
	v_trunc_f32_e32 v0, v0
	v_fma_f32 v1, -v0, v2, v1
	v_cvt_i32_f32_e32 v0, v0
	v_cmp_ge_f32_e64 s[8:9], |v1|, v2
	s_and_b64 s[8:9], s[8:9], exec
	s_cselect_b32 s6, s6, 0
	v_readfirstlane_b32 s8, v0
	s_add_i32 s6, s8, s6
	s_mul_i32 s8, s6, s12
	s_sub_i32 s8, s13, s8
	s_sext_i32_i8 s8, s8
	s_add_i32 s28, s11, s8
	s_ashr_i32 s29, s28, 31
	s_bfe_i64 s[12:13], s[6:7], 0x80000
	s_lshl_b64 s[8:9], s[28:29], 19
	s_lshl_b64 s[12:13], s[12:13], 19
	s_add_u32 s40, s35, s12
	s_addc_u32 s41, s50, s13
	s_add_i32 s29, s51, 0
	s_add_i32 m0, s29, 0x10000
	v_mov_b32_e32 v133, 0
	global_load_lds_dwordx4 v132, s[40:41]
	s_add_i32 m0, s29, 0x12000
	s_add_u32 s12, s40, 0x40000
	global_load_lds_dwordx4 v128, s[40:41]
	s_addc_u32 s13, s41, 0
	s_add_i32 m0, s29, 0x14000
	v_mov_b32_e32 v129, v133
	global_load_lds_dwordx4 v132, s[12:13]
	s_add_i32 m0, s29, 0x16000
	s_add_u32 s30, s48, s8
	s_addc_u32 s31, s49, s9
	s_add_i32 s52, s29, 0x2000
	global_load_lds_dwordx4 v128, s[12:13]
	s_mov_b32 m0, s29
	s_add_u32 s8, s30, 0x40000
	global_load_lds_dwordx4 v134, s[30:31]
	s_mov_b32 m0, s52
	s_addc_u32 s9, s31, 0
	s_add_i32 s53, s29, 0x4000
	global_load_lds_dwordx4 v130, s[30:31]
	s_mov_b32 m0, s53
	s_add_i32 s54, s29, 0x6000
	global_load_lds_dwordx4 v134, s[8:9]
	s_mov_b32 m0, s54
	v_mov_b32_e32 v135, v133
	global_load_lds_dwordx4 v130, s[8:9]
	v_mov_b32_e32 v131, v133
	s_cmp_eq_u32 s16, 1
	s_mov_b32 s55, 0
	v_lshl_add_u64 v[6:7], s[40:41], 0, v[132:133]
	v_lshl_add_u64 v[4:5], s[40:41], 0, v[128:129]
	v_lshl_add_u64 v[0:1], s[30:31], 0, v[134:135]
	s_cselect_b64 s[8:9], -1, 0
	s_cmp_lg_u32 s16, 1
	v_lshl_add_u64 v[2:3], s[30:31], 0, v[130:131]
	s_cbranch_scc1 .LBB0_178
	s_barrier

.LBB0_248:
	s_or_b64 exec, exec, s[6:7]
	s_waitcnt lgkmcnt(0)
	v_mov_b32_e32 v0, v206
	v_mov_b32_e32 v8, v206
	s_cmpk_lt_i32 s2, 0x404
	s_barrier
	s_cselect_b64 s[8:9], -1, 0
	v_lshrrev_b32_e32 v11, 6, v206
	v_and_b32_e32 v8, 63, v206
	s_load_dwordx2 s[96:97], s[0:1], 0x118
	v_readfirstlane_b32 s86, v11
	s_load_dwordx2 s[98:99], s[0:1], 0x8
	v_and_b32_e32 v9, 15, v8
	v_lshrrev_b32_e32 v10, 4, v8
	s_and_b32 s32, s86, 3
	s_lshr_b32 s101, s86, 2
	s_load_dwordx2 s[94:95], s[0:1], 0x110
	s_mov_b32 s87, s2
	v_lshlrev_b32_e32 v11, 4, v10
	s_mul_i32 s100, s101, 0xb00
	v_mov_b32_e32 v12, 0x1600
	v_mul_u32_u24_e32 v12, v9, v12
	v_mov_b32_e32 v14, 0x1600
	v_mul_u32_u24_e32 v14, v9, v14
	v_add_u32_e32 v12, v12, v11
	v_add_u32_e32 v14, v14, v11
	v_add_u32_e32 v12, s100, v12
	v_add_u32_e32 v14, s100, v14
	v_mov_b32_e32 v13, 0
	v_mov_b32_e32 v15, 0
	s_lshl_b32 s100, s32, 10
	s_add_u32 s100, s100, 0x20000
	v_lshlrev_b32_e32 v34, 4, v8
	v_add_u32_e32 v34, s100, v34
	s_lshl_b32 s100, s32, 8
	s_add_u32 s100, s100, 0x22000
	v_lshlrev_b32_e32 v35, 2, v8
	v_add_u32_e32 v35, s100, v35
	v_xor_b32_e32 v32, 16, v8
	v_lshlrev_b32_e32 v32, 2, v32
	v_xor_b32_e32 v33, 32, v8
	v_lshlrev_b32_e32 v33, 2, v33
	s_waitcnt lgkmcnt(0)
.Lsg_p2_loop:
	s_cmp_ge_u32 s87, 0x100
	s_cbranch_scc1 .Lsg_p2_done
	s_and_b32 s100, s87, 15
	s_lshl_b32 s100, s100, 4
	s_add_u32 s100, s100, 0x10000
	v_add_u32_e32 v24, s100, v9
	s_lshr_b32 s101, s87, 4
	s_lshl_b32 s101, s101, 6
	s_lshl_b32 vcc_lo, s32, 4
	s_add_u32 s101, s101, vcc_lo
	v_lshlrev_b32_e32 v25, 2, v10
	v_add_u32_e32 v25, s101, v25
	v_add_u32_e32 v26, 0xffff0000, v24
	v_lshlrev_b32_e32 v26, 10, v26
	v_add_u32_e32 v26, v26, v25
	v_lshlrev_b32_e32 v26, 2, v26
	s_add_u32 s88, s98, 0
	s_addc_u32 s89, s99, 0
	global_load_dwordx4 v[28:31], v26, s[88:89]
	s_mul_i32 vcc_lo, s100, 0x1600
	s_add_u32 s88, s96, vcc_lo
	s_addc_u32 s89, s97, 0
	s_add_u32 s88, s88, 0x11f00000
	s_addc_u32 s89, s89, 0
	s_mul_i32 vcc_lo, s101, 0x1600
	s_add_u32 s92, s96, vcc_lo
	s_addc_u32 s93, s97, 0
	s_add_u32 s92, s92, 0xd00000
	s_addc_u32 s93, s93, 0
	v_lshl_add_u64 v[0:1], s[88:89], 0, v[12:13]
	v_lshl_add_u64 v[2:3], s[92:93], 0, v[14:15]
	v_mov_b32_e32 v16, 0
	v_mov_b32_e32 v17, 0
	v_mov_b32_e32 v18, 0
	v_mov_b32_e32 v19, 0
	global_load_dwordx4 v[40:43], v[0:1], off
	global_load_dwordx4 v[44:47], v[2:3], off
	global_load_dwordx4 v[48:51], v[0:1], off offset:64
	global_load_dwordx4 v[52:55], v[2:3], off offset:64
	global_load_dwordx4 v[56:59], v[0:1], off offset:128
	global_load_dwordx4 v[60:63], v[2:3], off offset:128
	global_load_dwordx4 v[64:67], v[0:1], off offset:192
	global_load_dwordx4 v[68:71], v[2:3], off offset:192
	global_load_dwordx4 v[72:75], v[0:1], off offset:256
	global_load_dwordx4 v[76:79], v[2:3], off offset:256
	global_load_dwordx4 v[80:83], v[0:1], off offset:320
	global_load_dwordx4 v[84:87], v[2:3], off offset:320
	global_load_dwordx4 v[88:91], v[0:1], off offset:384
	global_load_dwordx4 v[92:95], v[2:3], off offset:384
	global_load_dwordx4 v[96:99], v[0:1], off offset:448
	global_load_dwordx4 v[100:103], v[2:3], off offset:448
	global_load_dwordx4 v[104:107], v[0:1], off offset:512
	global_load_dwordx4 v[108:111], v[2:3], off offset:512
	global_load_dwordx4 v[112:115], v[0:1], off offset:576
	global_load_dwordx4 v[116:119], v[2:3], off offset:576
	global_load_dwordx4 v[120:123], v[0:1], off offset:640
	global_load_dwordx4 v[124:127], v[2:3], off offset:640
	global_load_dwordx4 v[128:131], v[0:1], off offset:704
	global_load_dwordx4 v[132:135], v[2:3], off offset:704
	global_load_dwordx4 v[136:139], v[0:1], off offset:768
	global_load_dwordx4 v[140:143], v[2:3], off offset:768
	global_load_dwordx4 v[144:147], v[0:1], off offset:832
	global_load_dwordx4 v[148:151], v[2:3], off offset:832
	global_load_dwordx4 v[152:155], v[0:1], off offset:896
	global_load_dwordx4 v[156:159], v[2:3], off offset:896
	global_load_dwordx4 v[160:163], v[0:1], off offset:960
	global_load_dwordx4 v[164:167], v[2:3], off offset:960
	global_load_dwordx4 v[168:171], v[0:1], off offset:1024
	global_load_dwordx4 v[172:175], v[2:3], off offset:1024
	global_load_dwordx4 v[176:179], v[0:1], off offset:1088
	global_load_dwordx4 v[180:183], v[2:3], off offset:1088
	global_load_dwordx4 v[184:187], v[0:1], off offset:1152
	global_load_dwordx4 v[188:191], v[2:3], off offset:1152
	global_load_dwordx4 v[192:195], v[0:1], off offset:1216
	global_load_dwordx4 v[196:199], v[2:3], off offset:1216
	global_load_dwordx4 v[200:203], v[0:1], off offset:1280
	global_load_dwordx4 v[212:215], v[2:3], off offset:1280
	global_load_dwordx4 v[216:219], v[0:1], off offset:1344
	global_load_dwordx4 v[220:223], v[2:3], off offset:1344
	s_waitcnt vmcnt(42)
	v_mfma_f32_16x16x32_bf16 v[16:19], v[44:47], v[40:43], v[16:19]
	s_waitcnt vmcnt(40)
	v_mfma_f32_16x16x32_bf16 v[16:19], v[52:55], v[48:51], v[16:19]
	s_waitcnt vmcnt(38)
	v_mfma_f32_16x16x32_bf16 v[16:19], v[60:63], v[56:59], v[16:19]
	s_waitcnt vmcnt(36)
	v_mfma_f32_16x16x32_bf16 v[16:19], v[68:71], v[64:67], v[16:19]
	s_waitcnt vmcnt(34)
	v_mfma_f32_16x16x32_bf16 v[16:19], v[76:79], v[72:75], v[16:19]
	s_waitcnt vmcnt(32)
	v_mfma_f32_16x16x32_bf16 v[16:19], v[84:87], v[80:83], v[16:19]
	s_waitcnt vmcnt(30)
	v_mfma_f32_16x16x32_bf16 v[16:19], v[92:95], v[88:91], v[16:19]
	s_waitcnt vmcnt(28)
	v_mfma_f32_16x16x32_bf16 v[16:19], v[100:103], v[96:99], v[16:19]
	s_waitcnt vmcnt(26)
	v_mfma_f32_16x16x32_bf16 v[16:19], v[108:111], v[104:107], v[16:19]
	s_waitcnt vmcnt(24)
	v_mfma_f32_16x16x32_bf16 v[16:19], v[116:119], v[112:115], v[16:19]
	s_waitcnt vmcnt(22)
	v_mfma_f32_16x16x32_bf16 v[16:19], v[124:127], v[120:123], v[16:19]
	global_load_dwordx4 v[40:43], v[0:1], off offset:1408
	global_load_dwordx4 v[44:47], v[2:3], off offset:1408
	global_load_dwordx4 v[48:51], v[0:1], off offset:1472
	global_load_dwordx4 v[52:55], v[2:3], off offset:1472
	global_load_dwordx4 v[56:59], v[0:1], off offset:1536
	global_load_dwordx4 v[60:63], v[2:3], off offset:1536
	global_load_dwordx4 v[64:67], v[0:1], off offset:1600
	global_load_dwordx4 v[68:71], v[2:3], off offset:1600
	global_load_dwordx4 v[72:75], v[0:1], off offset:1664
	global_load_dwordx4 v[76:79], v[2:3], off offset:1664
	global_load_dwordx4 v[80:83], v[0:1], off offset:1728
	global_load_dwordx4 v[84:87], v[2:3], off offset:1728
	global_load_dwordx4 v[88:91], v[0:1], off offset:1792
	global_load_dwordx4 v[92:95], v[2:3], off offset:1792
	global_load_dwordx4 v[96:99], v[0:1], off offset:1856
	global_load_dwordx4 v[100:103], v[2:3], off offset:1856
	global_load_dwordx4 v[104:107], v[0:1], off offset:1920
	global_load_dwordx4 v[108:111], v[2:3], off offset:1920
	global_load_dwordx4 v[112:115], v[0:1], off offset:1984
	global_load_dwordx4 v[116:119], v[2:3], off offset:1984
	global_load_dwordx4 v[120:123], v[0:1], off offset:2048
	global_load_dwordx4 v[124:127], v[2:3], off offset:2048
	s_waitcnt vmcnt(42)
	v_mfma_f32_16x16x32_bf16 v[16:19], v[132:135], v[128:131], v[16:19]
	s_waitcnt vmcnt(40)
	v_mfma_f32_16x16x32_bf16 v[16:19], v[140:143], v[136:139], v[16:19]
	s_waitcnt vmcnt(38)
	v_mfma_f32_16x16x32_bf16 v[16:19], v[148:151], v[144:147], v[16:19]
	s_waitcnt vmcnt(36)
	v_mfma_f32_16x16x32_bf16 v[16:19], v[156:159], v[152:155], v[16:19]
	s_waitcnt vmcnt(34)
	v_mfma_f32_16x16x32_bf16 v[16:19], v[164:167], v[160:163], v[16:19]
	s_waitcnt vmcnt(32)
	v_mfma_f32_16x16x32_bf16 v[16:19], v[172:175], v[168:171], v[16:19]
	s_waitcnt vmcnt(30)
	v_mfma_f32_16x16x32_bf16 v[16:19], v[180:183], v[176:179], v[16:19]
	s_waitcnt vmcnt(28)
	v_mfma_f32_16x16x32_bf16 v[16:19], v[188:191], v[184:187], v[16:19]
	s_waitcnt vmcnt(26)
	v_mfma_f32_16x16x32_bf16 v[16:19], v[196:199], v[192:195], v[16:19]
	s_waitcnt vmcnt(24)
	v_mfma_f32_16x16x32_bf16 v[16:19], v[212:215], v[200:203], v[16:19]
	s_waitcnt vmcnt(22)
	v_mfma_f32_16x16x32_bf16 v[16:19], v[220:223], v[216:219], v[16:19]
	global_load_dwordx4 v[128:131], v[0:1], off offset:2112
	global_load_dwordx4 v[132:135], v[2:3], off offset:2112
	global_load_dwordx4 v[136:139], v[0:1], off offset:2176
	global_load_dwordx4 v[140:143], v[2:3], off offset:2176
	global_load_dwordx4 v[144:147], v[0:1], off offset:2240
	global_load_dwordx4 v[148:151], v[2:3], off offset:2240
	global_load_dwordx4 v[152:155], v[0:1], off offset:2304
	global_load_dwordx4 v[156:159], v[2:3], off offset:2304
	global_load_dwordx4 v[160:163], v[0:1], off offset:2368
	global_load_dwordx4 v[164:167], v[2:3], off offset:2368
	global_load_dwordx4 v[168:171], v[0:1], off offset:2432
	global_load_dwordx4 v[172:175], v[2:3], off offset:2432
	global_load_dwordx4 v[176:179], v[0:1], off offset:2496
	global_load_dwordx4 v[180:183], v[2:3], off offset:2496
	global_load_dwordx4 v[184:187], v[0:1], off offset:2560
	global_load_dwordx4 v[188:191], v[2:3], off offset:2560
	global_load_dwordx4 v[192:195], v[0:1], off offset:2624
	global_load_dwordx4 v[196:199], v[2:3], off offset:2624
	global_load_dwordx4 v[200:203], v[0:1], off offset:2688
	global_load_dwordx4 v[212:215], v[2:3], off offset:2688
	global_load_dwordx4 v[216:219], v[0:1], off offset:2752
	global_load_dwordx4 v[220:223], v[2:3], off offset:2752
	s_waitcnt vmcnt(42)
	v_mfma_f32_16x16x32_bf16 v[16:19], v[44:47], v[40:43], v[16:19]
	s_waitcnt vmcnt(40)
	v_mfma_f32_16x16x32_bf16 v[16:19], v[52:55], v[48:51], v[16:19]
	s_waitcnt vmcnt(38)
	v_mfma_f32_16x16x32_bf16 v[16:19], v[60:63], v[56:59], v[16:19]
	s_waitcnt vmcnt(36)
	v_mfma_f32_16x16x32_bf16 v[16:19], v[68:71], v[64:67], v[16:19]
	s_waitcnt vmcnt(34)
	v_mfma_f32_16x16x32_bf16 v[16:19], v[76:79], v[72:75], v[16:19]
	s_waitcnt vmcnt(32)
	v_mfma_f32_16x16x32_bf16 v[16:19], v[84:87], v[80:83], v[16:19]
	s_waitcnt vmcnt(30)
	v_mfma_f32_16x16x32_bf16 v[16:19], v[92:95], v[88:91], v[16:19]
	s_waitcnt vmcnt(28)
	v_mfma_f32_16x16x32_bf16 v[16:19], v[100:103], v[96:99], v[16:19]
	s_waitcnt vmcnt(26)
	v_mfma_f32_16x16x32_bf16 v[16:19], v[108:111], v[104:107], v[16:19]
	s_waitcnt vmcnt(24)
	v_mfma_f32_16x16x32_bf16 v[16:19], v[116:119], v[112:115], v[16:19]
	s_waitcnt vmcnt(22)
	v_mfma_f32_16x16x32_bf16 v[16:19], v[124:127], v[120:123], v[16:19]
	s_waitcnt vmcnt(20)
	v_mfma_f32_16x16x32_bf16 v[16:19], v[132:135], v[128:131], v[16:19]
	s_waitcnt vmcnt(18)
	v_mfma_f32_16x16x32_bf16 v[16:19], v[140:143], v[136:139], v[16:19]
	s_waitcnt vmcnt(16)
	v_mfma_f32_16x16x32_bf16 v[16:19], v[148:151], v[144:147], v[16:19]
	s_waitcnt vmcnt(14)
	v_mfma_f32_16x16x32_bf16 v[16:19], v[156:159], v[152:155], v[16:19]
	s_waitcnt vmcnt(12)
	v_mfma_f32_16x16x32_bf16 v[16:19], v[164:167], v[160:163], v[16:19]
	s_waitcnt vmcnt(10)
	v_mfma_f32_16x16x32_bf16 v[16:19], v[172:175], v[168:171], v[16:19]
	s_waitcnt vmcnt(8)
	v_mfma_f32_16x16x32_bf16 v[16:19], v[180:183], v[176:179], v[16:19]
	s_waitcnt vmcnt(6)
	v_mfma_f32_16x16x32_bf16 v[16:19], v[188:191], v[184:187], v[16:19]
	s_waitcnt vmcnt(4)
	v_mfma_f32_16x16x32_bf16 v[16:19], v[196:199], v[192:195], v[16:19]
	s_waitcnt vmcnt(2)
	v_mfma_f32_16x16x32_bf16 v[16:19], v[212:215], v[200:203], v[16:19]
	s_waitcnt vmcnt(0)
	v_mfma_f32_16x16x32_bf16 v[16:19], v[220:223], v[216:219], v[16:19]
	s_nop 7
	s_nop 7
	s_lshr_b32 s101, s86, 2
	s_cmp_eq_u32 s101, 1
	s_cbranch_scc0 .Lsg_p2_nowr
	ds_write_b128 v34, v[16:19]
.Lsg_p2_nowr:
	s_waitcnt lgkmcnt(0)
	s_barrier
	s_cmp_eq_u32 s101, 0
	s_cbranch_scc0 .Lsg_p2_noepi
	ds_read_b128 v[40:43], v34
	s_waitcnt lgkmcnt(0)
	v_add_f32_e32 v16, v16, v40
	v_add_f32_e32 v17, v17, v41
	v_add_f32_e32 v18, v18, v42
	v_add_f32_e32 v19, v19, v43
	v_lshlrev_b32_e32 v27, 10, v24
	v_add_u32_e32 v27, v27, v25
	v_fma_f32 v28, v16, 0.5, v28
	v_fma_f32 v29, v17, 0.5, v29
	v_fma_f32 v30, v18, 0.5, v30
	v_fma_f32 v31, v19, 0.5, v31
	v_lshlrev_b32_e32 v26, 2, v27
	global_store_dwordx4 v26, v[28:31], s[94:95]
	v_cvt_pk_bf16_f32 v40, v28, v29
	v_cvt_pk_bf16_f32 v41, v30, v31
	v_lshlrev_b32_e32 v26, 1, v27
	s_add_u32 s92, s96, 0x9e00000
	s_addc_u32 s93, s97, 0
	global_store_dwordx2 v26, v[40:41], s[92:93]
	v_mul_f32_e32 v42, v28, v28
	v_fmac_f32_e32 v42, v29, v29
	v_fmac_f32_e32 v42, v30, v30
	v_fmac_f32_e32 v42, v31, v31
	s_nop 1
	ds_bpermute_b32 v43, v32, v42
	s_waitcnt lgkmcnt(0)
	v_add_f32_e32 v42, v42, v43
	s_nop 1
	ds_bpermute_b32 v43, v33, v42
	s_waitcnt lgkmcnt(0)
	v_add_f32_e32 v42, v42, v43
	s_nop 1
	ds_write_b32 v35, v42

.Lsg_p2_done:
	v_mov_b32_e32 v0, v206
	v_mov_b32_e32 v8, v206
	s_nop 1
	s_cmpk_gt_i32 s2, 0x403
	v_readfirstlane_b32 s10, v8
	s_cbranch_scc1 .LBB0_254
	s_lshr_b32 s6, s3, 29
	s_add_i32 s11, s2, s6
	s_and_b32 s6, s11, -8
	s_sub_i32 s12, s2, s6
	s_cmp_gt_i32 s12, 3
	s_cbranch_scc0 .LBB0_251
	s_lshl_b32 s6, s12, 7
	s_or_b32 s13, s6, 0
	s_cbranch_execz .LBB0_252
	s_branch .LBB0_253

.LBB0_399:
	s_or_b64 exec, exec, s[8:9]
	v_mov_b32_e32 v128, v206
	v_mov_b32_e32 v8, v206
	s_waitcnt lgkmcnt(0)
	v_cndmask_b32_e64 v0, 0, 1, s[14:15]
	s_barrier
	v_lshrrev_b32_e32 v11, 6, v206
	v_and_b32_e32 v8, 63, v206
	s_load_dwordx2 s[96:97], s[0:1], 0x118
	v_readfirstlane_b32 s86, v11
	v_and_b32_e32 v9, 15, v8
	v_lshrrev_b32_e32 v10, 4, v8
	s_mov_b32 s32, s86
	s_mov_b32 s101, 0
	s_mov_b32 s87, s2
	v_lshlrev_b32_e32 v11, 4, v10
	s_mul_i32 s100, s101, 0x400
	v_mov_b32_e32 v12, 0x800
	v_mul_u32_u24_e32 v12, v9, v12
	v_mov_b32_e32 v14, 0x800
	v_mul_u32_u24_e32 v14, v9, v14
	v_add_u32_e32 v12, v12, v11
	v_add_u32_e32 v14, v14, v11
	v_add_u32_e32 v12, s100, v12
	v_add_u32_e32 v14, s100, v14
	v_mov_b32_e32 v13, 0
	v_mov_b32_e32 v15, 0
	s_lshl_b32 s100, s32, 10
	s_add_u32 s100, s100, 0x20000
	v_lshlrev_b32_e32 v34, 4, v8
	v_add_u32_e32 v34, s100, v34
	s_lshl_b32 s100, s32, 8
	s_add_u32 s100, s100, 0x22000
	v_lshlrev_b32_e32 v35, 2, v8
	v_add_u32_e32 v35, s100, v35
	v_xor_b32_e32 v32, 16, v8
	v_lshlrev_b32_e32 v32, 2, v32
	v_xor_b32_e32 v33, 32, v8
	v_lshlrev_b32_e32 v33, 2, v33
	s_waitcnt lgkmcnt(0)
.Lsg_p3_loop:
	s_cmp_ge_u32 s87, 0x2c0
	s_cbranch_scc1 .Lsg_p3_done
	s_and_b32 s100, s87, 15
	s_lshl_b32 s100, s100, 4
	s_add_u32 s100, s100, 0x10000
	v_add_u32_e32 v24, s100, v9
	s_lshr_b32 s101, s87, 4
	s_lshl_b32 s101, s101, 7
	s_lshl_b32 vcc_lo, s32, 4
	s_add_u32 s101, s101, vcc_lo
	v_lshlrev_b32_e32 v25, 2, v10
	v_add_u32_e32 v25, s101, v25
	s_add_u32 s88, s96, 0x4600000
	s_addc_u32 s89, s97, 0
	v_lshlrev_b32_e32 v26, 6, v24
	v_lshl_add_u32 v26, v10, 4, v26
	global_load_dwordx4 v[28:31], v26, s[88:89]
	s_mul_i32 vcc_lo, s100, 0x800
	s_add_u32 s88, s96, vcc_lo
	s_addc_u32 s89, s97, 0
	s_add_u32 s88, s88, 0x9e00000
	s_addc_u32 s89, s89, 0
	s_mul_i32 vcc_lo, s101, 0x800
	s_add_u32 s92, s96, vcc_lo
	s_addc_u32 s93, s97, 0
	s_add_u32 s92, s92, 0x1300000
	s_addc_u32 s93, s93, 0
	v_lshl_add_u64 v[0:1], s[88:89], 0, v[12:13]
	v_lshl_add_u64 v[2:3], s[92:93], 0, v[14:15]
	v_mov_b32_e32 v16, 0
	v_mov_b32_e32 v17, 0
	v_mov_b32_e32 v18, 0
	v_mov_b32_e32 v19, 0
	global_load_dwordx4 v[40:43], v[0:1], off
	global_load_dwordx4 v[44:47], v[2:3], off
	global_load_dwordx4 v[48:51], v[0:1], off offset:64
	global_load_dwordx4 v[52:55], v[2:3], off offset:64
	global_load_dwordx4 v[56:59], v[0:1], off offset:128
	global_load_dwordx4 v[60:63], v[2:3], off offset:128
	global_load_dwordx4 v[64:67], v[0:1], off offset:192
	global_load_dwordx4 v[68:71], v[2:3], off offset:192
	global_load_dwordx4 v[72:75], v[0:1], off offset:256
	global_load_dwordx4 v[76:79], v[2:3], off offset:256
	global_load_dwordx4 v[80:83], v[0:1], off offset:320
	global_load_dwordx4 v[84:87], v[2:3], off offset:320
	global_load_dwordx4 v[88:91], v[0:1], off offset:384
	global_load_dwordx4 v[92:95], v[2:3], off offset:384
	global_load_dwordx4 v[96:99], v[0:1], off offset:448
	global_load_dwordx4 v[100:103], v[2:3], off offset:448
	global_load_dwordx4 v[104:107], v[0:1], off offset:512
	global_load_dwordx4 v[108:111], v[2:3], off offset:512
	global_load_dwordx4 v[112:115], v[0:1], off offset:576
	global_load_dwordx4 v[116:119], v[2:3], off offset:576
	global_load_dwordx4 v[120:123], v[0:1], off offset:640
	global_load_dwordx4 v[124:127], v[2:3], off offset:640
	global_load_dwordx4 v[128:131], v[0:1], off offset:704
	global_load_dwordx4 v[132:135], v[2:3], off offset:704
	global_load_dwordx4 v[136:139], v[0:1], off offset:768
	global_load_dwordx4 v[140:143], v[2:3], off offset:768
	global_load_dwordx4 v[144:147], v[0:1], off offset:832
	global_load_dwordx4 v[148:151], v[2:3], off offset:832
	global_load_dwordx4 v[152:155], v[0:1], off offset:896
	global_load_dwordx4 v[156:159], v[2:3], off offset:896
	global_load_dwordx4 v[160:163], v[0:1], off offset:960
	global_load_dwordx4 v[164:167], v[2:3], off offset:960
	global_load_dwordx4 v[168:171], v[0:1], off offset:1024
	global_load_dwordx4 v[172:175], v[2:3], off offset:1024
	global_load_dwordx4 v[176:179], v[0:1], off offset:1088
	global_load_dwordx4 v[180:183], v[2:3], off offset:1088
	global_load_dwordx4 v[184:187], v[0:1], off offset:1152
	global_load_dwordx4 v[188:191], v[2:3], off offset:1152
	global_load_dwordx4 v[192:195], v[0:1], off offset:1216
	global_load_dwordx4 v[196:199], v[2:3], off offset:1216
	global_load_dwordx4 v[200:203], v[0:1], off offset:1280
	global_load_dwordx4 v[212:215], v[2:3], off offset:1280
	global_load_dwordx4 v[216:219], v[0:1], off offset:1344
	global_load_dwordx4 v[220:223], v[2:3], off offset:1344
	global_load_dwordx4 v[224:227], v[0:1], off offset:1408
	global_load_dwordx4 v[228:231], v[2:3], off offset:1408
	global_load_dwordx4 v[232:235], v[0:1], off offset:1472
	global_load_dwordx4 v[236:239], v[2:3], off offset:1472
	global_load_dwordx4 v[240:243], v[0:1], off offset:1536
	global_load_dwordx4 v[244:247], v[2:3], off offset:1536
	global_load_dwordx4 v[248:251], v[0:1], off offset:1600
	global_load_dwordx4 v[252:255], v[2:3], off offset:1600
	s_waitcnt vmcnt(50)
	v_mfma_f32_16x16x32_bf16 v[16:19], v[44:47], v[40:43], v[16:19]
	s_waitcnt vmcnt(48)
	v_mfma_f32_16x16x32_bf16 v[16:19], v[52:55], v[48:51], v[16:19]
	s_waitcnt vmcnt(46)
	v_mfma_f32_16x16x32_bf16 v[16:19], v[60:63], v[56:59], v[16:19]
	s_waitcnt vmcnt(44)
	v_mfma_f32_16x16x32_bf16 v[16:19], v[68:71], v[64:67], v[16:19]
	s_waitcnt vmcnt(42)
	v_mfma_f32_16x16x32_bf16 v[16:19], v[76:79], v[72:75], v[16:19]
	s_waitcnt vmcnt(40)
	v_mfma_f32_16x16x32_bf16 v[16:19], v[84:87], v[80:83], v[16:19]
	s_waitcnt vmcnt(38)
	v_mfma_f32_16x16x32_bf16 v[16:19], v[92:95], v[88:91], v[16:19]
	s_waitcnt vmcnt(36)
	v_mfma_f32_16x16x32_bf16 v[16:19], v[100:103], v[96:99], v[16:19]
	s_waitcnt vmcnt(34)
	v_mfma_f32_16x16x32_bf16 v[16:19], v[108:111], v[104:107], v[16:19]
	s_waitcnt vmcnt(32)
	v_mfma_f32_16x16x32_bf16 v[16:19], v[116:119], v[112:115], v[16:19]
	s_waitcnt vmcnt(30)
	v_mfma_f32_16x16x32_bf16 v[16:19], v[124:127], v[120:123], v[16:19]
	s_waitcnt vmcnt(28)
	v_mfma_f32_16x16x32_bf16 v[16:19], v[132:135], v[128:131], v[16:19]
	s_waitcnt vmcnt(26)
	v_mfma_f32_16x16x32_bf16 v[16:19], v[140:143], v[136:139], v[16:19]
	global_load_dwordx4 v[40:43], v[0:1], off offset:1664
	global_load_dwordx4 v[44:47], v[2:3], off offset:1664
	global_load_dwordx4 v[48:51], v[0:1], off offset:1728
	global_load_dwordx4 v[52:55], v[2:3], off offset:1728
	global_load_dwordx4 v[56:59], v[0:1], off offset:1792
	global_load_dwordx4 v[60:63], v[2:3], off offset:1792
	global_load_dwordx4 v[64:67], v[0:1], off offset:1856
	global_load_dwordx4 v[68:71], v[2:3], off offset:1856
	global_load_dwordx4 v[72:75], v[0:1], off offset:1920
	global_load_dwordx4 v[76:79], v[2:3], off offset:1920
	global_load_dwordx4 v[80:83], v[0:1], off offset:1984
	global_load_dwordx4 v[84:87], v[2:3], off offset:1984
	s_waitcnt vmcnt(36)
	v_mfma_f32_16x16x32_bf16 v[16:19], v[148:151], v[144:147], v[16:19]
	s_waitcnt vmcnt(34)
	v_mfma_f32_16x16x32_bf16 v[16:19], v[156:159], v[152:155], v[16:19]
	s_waitcnt vmcnt(32)
	v_mfma_f32_16x16x32_bf16 v[16:19], v[164:167], v[160:163], v[16:19]
	s_waitcnt vmcnt(30)
	v_mfma_f32_16x16x32_bf16 v[16:19], v[172:175], v[168:171], v[16:19]
	s_waitcnt vmcnt(28)
	v_mfma_f32_16x16x32_bf16 v[16:19], v[180:183], v[176:179], v[16:19]
	s_waitcnt vmcnt(26)
	v_mfma_f32_16x16x32_bf16 v[16:19], v[188:191], v[184:187], v[16:19]
	s_waitcnt vmcnt(24)
	v_mfma_f32_16x16x32_bf16 v[16:19], v[196:199], v[192:195], v[16:19]
	s_waitcnt vmcnt(22)
	v_mfma_f32_16x16x32_bf16 v[16:19], v[212:215], v[200:203], v[16:19]
	s_waitcnt vmcnt(20)
	v_mfma_f32_16x16x32_bf16 v[16:19], v[220:223], v[216:219], v[16:19]
	s_waitcnt vmcnt(18)
	v_mfma_f32_16x16x32_bf16 v[16:19], v[228:231], v[224:227], v[16:19]
	s_waitcnt vmcnt(16)
	v_mfma_f32_16x16x32_bf16 v[16:19], v[236:239], v[232:235], v[16:19]
	s_waitcnt vmcnt(14)
	v_mfma_f32_16x16x32_bf16 v[16:19], v[244:247], v[240:243], v[16:19]
	s_waitcnt vmcnt(12)
	v_mfma_f32_16x16x32_bf16 v[16:19], v[252:255], v[248:251], v[16:19]
	s_waitcnt vmcnt(10)
	v_mfma_f32_16x16x32_bf16 v[16:19], v[44:47], v[40:43], v[16:19]
	s_waitcnt vmcnt(8)
	v_mfma_f32_16x16x32_bf16 v[16:19], v[52:55], v[48:51], v[16:19]
	s_waitcnt vmcnt(6)
	v_mfma_f32_16x16x32_bf16 v[16:19], v[60:63], v[56:59], v[16:19]
	s_waitcnt vmcnt(4)
	v_mfma_f32_16x16x32_bf16 v[16:19], v[68:71], v[64:67], v[16:19]
	s_waitcnt vmcnt(2)
	v_mfma_f32_16x16x32_bf16 v[16:19], v[76:79], v[72:75], v[16:19]
	s_waitcnt vmcnt(0)
	v_mfma_f32_16x16x32_bf16 v[16:19], v[84:87], v[80:83], v[16:19]
	s_nop 7
	s_nop 7
	v_add_f32_e32 v28, v28, v29
	v_add_f32_e32 v30, v30, v31
	v_add_f32_e32 v28, v28, v30
	s_nop 1
	ds_bpermute_b32 v29, v32, v28
	s_waitcnt lgkmcnt(0)
	v_add_f32_e32 v28, v28, v29
	s_nop 1
	ds_bpermute_b32 v29, v33, v28
	s_waitcnt lgkmcnt(0)
	v_add_f32_e32 v28, v28, v29
	v_mov_b32_e32 v29, 0x358637bd
	s_mov_b32 s101, 0x3a800000
	v_fma_f32 v28, v28, s101, v29
	v_rsq_f32_e32 v28, v28
	s_nop 1
	v_mul_f32_e32 v16, v16, v28
	v_mul_f32_e32 v17, v17, v28
	v_mul_f32_e32 v18, v18, v28
	v_mul_f32_e32 v19, v19, v28
	v_cvt_pk_bf16_f32 v40, v16, v17
	v_cvt_pk_bf16_f32 v41, v18, v19
	v_mov_b32_e32 v26, 0x2c00
	v_mul_u32_u24_e32 v26, v24, v26
	v_lshl_add_u32 v26, v25, 1, v26
	s_add_u32 s92, s96, 0x11f00000
	s_addc_u32 s93, s97, 0
	global_store_dwordx2 v26, v[40:41], s[92:93]

.Lsg_p3_done:
	v_mov_b32_e32 v128, v206
	v_mov_b32_e32 v8, v206
	v_cndmask_b32_e64 v0, 0, 1, s[14:15]
	s_nop 1
	v_cmp_ne_u32_e64 s[8:9], 1, v0
	v_readfirstlane_b32 s35, v128
	s_andn2_b64 vcc, exec, s[14:15]
	v_readfirstlane_b32 s18, v8
	s_cbranch_vccnz .LBB0_423
	s_lshr_b32 s10, s3, 29
	s_add_i32 s13, s2, s10
	s_and_b32 s10, s13, -8
	s_sub_i32 s14, s2, s10
	s_cmp_gt_i32 s14, 5
	s_cbranch_scc0 .LBB0_402
	s_mul_i32 s10, s14, 0x2c0
	s_add_i32 s12, s10, 0
	s_cbranch_execz .LBB0_403
	s_branch .LBB0_404

.Lsg_p5_loop:
	s_cmp_ge_u32 s87, 0x100
	s_cbranch_scc1 .Lsg_p5_done
	s_and_b32 s100, s87, 15
	s_lshl_b32 s100, s100, 4
	s_add_u32 s100, s100, 0x10000
	v_add_u32_e32 v24, s100, v9
	s_lshr_b32 s101, s87, 4
	s_lshl_b32 s101, s101, 6
	s_lshl_b32 vcc_lo, s32, 4
	s_add_u32 s101, s101, vcc_lo
	v_lshlrev_b32_e32 v25, 2, v10
	v_add_u32_e32 v25, s101, v25
	v_mov_b32_e32 v26, 0x2c00
	v_mul_u32_u24_e32 v26, v24, v26
	v_lshl_add_u32 v26, v25, 1, v26
	s_add_u32 s88, s96, 0x11f01c00
	s_addc_u32 s89, s97, 0
	global_load_dwordx2 v[28:29], v26, s[88:89]
	global_load_dwordx2 v[30:31], v26, s[88:89] offset:2048
	s_mul_i32 vcc_lo, s100, 0x2c00
	s_add_u32 s88, s96, vcc_lo
	s_addc_u32 s89, s97, 0
	s_add_u32 s88, s88, 0x11f00000
	s_addc_u32 s89, s89, 0
	s_mul_i32 vcc_lo, s101, 0x400
	s_add_u32 s92, s96, vcc_lo
	s_addc_u32 s93, s97, 0
	s_add_u32 s92, s92, 0x1f00000
	s_addc_u32 s93, s93, 0
	s_mul_i32 vcc_lo, s100, 0x2c00
	s_add_u32 s90, s96, vcc_lo
	s_addc_u32 s91, s97, 0
	s_add_u32 s90, s90, 0x11f01800
	s_addc_u32 s91, s91, 0
	s_mul_i32 vcc_lo, s101, 0x400
	s_add_u32 s94, s96, vcc_lo
	s_addc_u32 s95, s97, 0
	s_add_u32 s94, s94, 0x2000000
	s_addc_u32 s95, s95, 0
	v_lshl_add_u64 v[0:1], s[88:89], 0, v[12:13]
	v_lshl_add_u64 v[2:3], s[92:93], 0, v[14:15]
	v_lshl_add_u64 v[4:5], s[90:91], 0, v[36:37]
	v_lshl_add_u64 v[6:7], s[94:95], 0, v[38:39]
	v_mov_b32_e32 v16, 0
	v_mov_b32_e32 v17, 0
	v_mov_b32_e32 v18, 0
	v_mov_b32_e32 v19, 0
	v_mov_b32_e32 v20, 0
	v_mov_b32_e32 v21, 0
	v_mov_b32_e32 v22, 0
	v_mov_b32_e32 v23, 0
	global_load_dwordx4 v[40:43], v[0:1], off
	global_load_dwordx4 v[44:47], v[2:3], off
	global_load_dwordx4 v[48:51], v[4:5], off
	global_load_dwordx4 v[52:55], v[6:7], off
	global_load_dwordx4 v[56:59], v[0:1], off offset:64
	global_load_dwordx4 v[60:63], v[2:3], off offset:64
	global_load_dwordx4 v[64:67], v[4:5], off offset:64
	global_load_dwordx4 v[68:71], v[6:7], off offset:64
	global_load_dwordx4 v[72:75], v[0:1], off offset:128
	global_load_dwordx4 v[76:79], v[2:3], off offset:128
	global_load_dwordx4 v[80:83], v[4:5], off offset:128
	global_load_dwordx4 v[84:87], v[6:7], off offset:128
	global_load_dwordx4 v[88:91], v[0:1], off offset:192
	global_load_dwordx4 v[92:95], v[2:3], off offset:192
	global_load_dwordx4 v[96:99], v[4:5], off offset:192
	global_load_dwordx4 v[100:103], v[6:7], off offset:192
	global_load_dwordx4 v[104:107], v[0:1], off offset:256
	global_load_dwordx4 v[108:111], v[2:3], off offset:256
	global_load_dwordx4 v[112:115], v[4:5], off offset:256
	global_load_dwordx4 v[116:119], v[6:7], off offset:256
	global_load_dwordx4 v[120:123], v[0:1], off offset:320
	global_load_dwordx4 v[124:127], v[2:3], off offset:320
	global_load_dwordx4 v[128:131], v[4:5], off offset:320
	global_load_dwordx4 v[132:135], v[6:7], off offset:320
	global_load_dwordx4 v[136:139], v[0:1], off offset:384
	global_load_dwordx4 v[140:143], v[2:3], off offset:384
	global_load_dwordx4 v[144:147], v[4:5], off offset:384
	global_load_dwordx4 v[148:151], v[6:7], off offset:384
	global_load_dwordx4 v[152:155], v[0:1], off offset:448
	global_load_dwordx4 v[156:159], v[2:3], off offset:448
	global_load_dwordx4 v[160:163], v[4:5], off offset:448
	global_load_dwordx4 v[164:167], v[6:7], off offset:448
	s_waitcnt vmcnt(28)
	v_mfma_f32_16x16x32_bf16 v[16:19], v[44:47], v[40:43], v[16:19]
	v_mfma_f32_16x16x32_bf16 v[20:23], v[52:55], v[48:51], v[20:23]
	s_waitcnt vmcnt(24)
	v_mfma_f32_16x16x32_bf16 v[16:19], v[60:63], v[56:59], v[16:19]
	v_mfma_f32_16x16x32_bf16 v[20:23], v[68:71], v[64:67], v[20:23]
	s_waitcnt vmcnt(20)
	v_mfma_f32_16x16x32_bf16 v[16:19], v[76:79], v[72:75], v[16:19]
	v_mfma_f32_16x16x32_bf16 v[20:23], v[84:87], v[80:83], v[20:23]
	s_waitcnt vmcnt(16)
	v_mfma_f32_16x16x32_bf16 v[16:19], v[92:95], v[88:91], v[16:19]
	v_mfma_f32_16x16x32_bf16 v[20:23], v[100:103], v[96:99], v[20:23]
	s_waitcnt vmcnt(12)
	v_mfma_f32_16x16x32_bf16 v[16:19], v[108:111], v[104:107], v[16:19]
	v_mfma_f32_16x16x32_bf16 v[20:23], v[116:119], v[112:115], v[20:23]
	s_waitcnt vmcnt(8)
	v_mfma_f32_16x16x32_bf16 v[16:19], v[124:127], v[120:123], v[16:19]
	v_mfma_f32_16x16x32_bf16 v[20:23], v[132:135], v[128:131], v[20:23]
	s_waitcnt vmcnt(4)
	v_mfma_f32_16x16x32_bf16 v[16:19], v[140:143], v[136:139], v[16:19]
	v_mfma_f32_16x16x32_bf16 v[20:23], v[148:151], v[144:147], v[20:23]
	s_waitcnt vmcnt(0)
	v_mfma_f32_16x16x32_bf16 v[16:19], v[156:159], v[152:155], v[16:19]
	v_mfma_f32_16x16x32_bf16 v[20:23], v[164:167], v[160:163], v[20:23]
	s_nop 7
	s_nop 7
	s_lshr_b32 s101, s86, 2
	s_cmp_eq_u32 s101, 1
	s_cbranch_scc0 .Lsg_p5_nowr
	ds_write_b128 v34, v[16:19]
	ds_write_b128 v34, v[20:23] offset:4096
.Lsg_p5_nowr:
	s_waitcnt lgkmcnt(0)
	s_barrier
	s_cmp_eq_u32 s101, 0
	s_cbranch_scc0 .Lsg_p5_noepi
	ds_read_b128 v[40:43], v34
	ds_read_b128 v[44:47], v34 offset:4096
	s_waitcnt lgkmcnt(0)
	v_add_f32_e32 v16, v16, v40
	v_add_f32_e32 v17, v17, v41
	v_add_f32_e32 v18, v18, v42
	v_add_f32_e32 v19, v19, v43
	v_add_f32_e32 v20, v20, v44
	v_add_f32_e32 v21, v21, v45
	v_add_f32_e32 v22, v22, v46
	v_add_f32_e32 v23, v23, v47
	v_lshlrev_b32_e32 v44, 16, v28
	v_and_b32_e32 v45, 0xffff0000, v28
	v_lshlrev_b32_e32 v46, 16, v29
	v_and_b32_e32 v47, 0xffff0000, v29
	v_lshlrev_b32_e32 v48, 16, v30
	v_and_b32_e32 v49, 0xffff0000, v30
	v_lshlrev_b32_e32 v50, 16, v31
	v_and_b32_e32 v51, 0xffff0000, v31
	v_mul_f32_e32 v44, 0xbfb8aa3b, v44
	v_mul_f32_e32 v45, 0xbfb8aa3b, v45
	v_mul_f32_e32 v46, 0xbfb8aa3b, v46
	v_mul_f32_e32 v47, 0xbfb8aa3b, v47
	v_mul_f32_e32 v48, 0xbfb8aa3b, v48
	v_mul_f32_e32 v49, 0xbfb8aa3b, v49
	v_mul_f32_e32 v50, 0xbfb8aa3b, v50
	v_mul_f32_e32 v51, 0xbfb8aa3b, v51
	v_exp_f32_e32 v44, v44
	v_exp_f32_e32 v45, v45
	v_exp_f32_e32 v46, v46
	v_exp_f32_e32 v47, v47
	v_exp_f32_e32 v48, v48
	v_exp_f32_e32 v49, v49
	v_exp_f32_e32 v50, v50
	v_exp_f32_e32 v51, v51
	s_nop 1
	v_add_f32_e32 v44, 1.0, v44
	v_add_f32_e32 v45, 1.0, v45
	v_add_f32_e32 v46, 1.0, v46
	v_add_f32_e32 v47, 1.0, v47
	v_add_f32_e32 v48, 1.0, v48
	v_add_f32_e32 v49, 1.0, v49
	v_add_f32_e32 v50, 1.0, v50
	v_add_f32_e32 v51, 1.0, v51
	v_rcp_f32_e32 v44, v44
	v_rcp_f32_e32 v45, v45
	v_rcp_f32_e32 v46, v46
	v_rcp_f32_e32 v47, v47
	v_rcp_f32_e32 v48, v48
	v_rcp_f32_e32 v49, v49
	v_rcp_f32_e32 v50, v50
	v_rcp_f32_e32 v51, v51
	s_nop 1
	v_mul_f32_e32 v44, v44, v16
	v_fmac_f32_e32 v44, v48, v20
	v_mul_f32_e32 v45, v45, v17
	v_fmac_f32_e32 v45, v49, v21
	v_mul_f32_e32 v46, v46, v18
	v_fmac_f32_e32 v46, v50, v22
	v_mul_f32_e32 v47, v47, v19
	v_fmac_f32_e32 v47, v51, v23
	v_cvt_pk_bf16_f32 v40, v44, v45
	v_cvt_pk_bf16_f32 v41, v46, v47
	s_add_u32 s92, s96, 0x11f00400
	s_addc_u32 s93, s97, 0
	global_store_dwordx2 v26, v[40:41], s[92:93]

.Lsg_p5_done:
	v_mov_b32_e32 v0, v206
	v_mov_b32_e32 v8, v206
	s_nop 1
	s_and_b64 vcc, exec, s[6:7]
	v_readfirstlane_b32 s12, v8
	s_cbranch_vccnz .LBB0_908
	s_lshr_b32 s10, s3, 29
	s_add_i32 s13, s2, s10
	s_and_b32 s10, s13, -8
	s_sub_i32 s15, s2, s10
	s_cmp_gt_i32 s15, 3
	s_cbranch_scc0 .LBB0_885
	s_lshl_b32 s10, s15, 7
	s_or_b32 s14, s10, 0
	s_cbranch_execz .LBB0_886
	s_branch .LBB0_887

.LBB0_986:
	s_or_b64 exec, exec, s[10:11]
	s_waitcnt lgkmcnt(0)
	v_mov_b32_e32 v0, v206
	v_mov_b32_e32 v8, v206
	s_barrier
	v_lshrrev_b32_e32 v11, 6, v206
	v_and_b32_e32 v8, 63, v206
	s_load_dwordx2 s[96:97], s[0:1], 0x118
	v_readfirstlane_b32 s86, v11
	s_load_dwordx2 s[98:99], s[0:1], 0x110
	v_and_b32_e32 v9, 15, v8
	v_lshrrev_b32_e32 v10, 4, v8
	s_and_b32 s32, s86, 3
	s_lshr_b32 s101, s86, 2
	s_load_dwordx2 s[94:95], s[0:1], 0x110
	s_mov_b32 s87, s2
	v_lshlrev_b32_e32 v11, 4, v10
	s_mul_i32 s100, s101, 0x400
	v_mov_b32_e32 v12, 0x2c00
	v_mul_u32_u24_e32 v12, v9, v12
	v_mov_b32_e32 v14, 0x800
	v_mul_u32_u24_e32 v14, v9, v14
	v_add_u32_e32 v12, v12, v11
	v_add_u32_e32 v14, v14, v11
	v_add_u32_e32 v12, s100, v12
	v_add_u32_e32 v14, s100, v14
	v_mov_b32_e32 v13, 0
	v_mov_b32_e32 v15, 0
	s_lshl_b32 s100, s32, 10
	s_add_u32 s100, s100, 0x20000
	v_lshlrev_b32_e32 v34, 4, v8
	v_add_u32_e32 v34, s100, v34
	s_lshl_b32 s100, s32, 8
	s_add_u32 s100, s100, 0x22000
	v_lshlrev_b32_e32 v35, 2, v8
	v_add_u32_e32 v35, s100, v35
	v_xor_b32_e32 v32, 16, v8
	v_lshlrev_b32_e32 v32, 2, v32
	v_xor_b32_e32 v33, 32, v8
	v_lshlrev_b32_e32 v33, 2, v33
	s_waitcnt lgkmcnt(0)
.Lsg_p6_loop:
	s_cmp_ge_u32 s87, 0x100
	s_cbranch_scc1 .Lsg_p6_done
	s_and_b32 s100, s87, 15
	s_lshl_b32 s100, s100, 4
	s_add_u32 s100, s100, 0x10000
	v_add_u32_e32 v24, s100, v9
	s_lshr_b32 s101, s87, 4
	s_lshl_b32 s101, s101, 6
	s_lshl_b32 vcc_lo, s32, 4
	s_add_u32 s101, s101, vcc_lo
	v_lshlrev_b32_e32 v25, 2, v10
	v_add_u32_e32 v25, s101, v25
	v_add_u32_e32 v26, 0, v24
	v_lshlrev_b32_e32 v26, 10, v26
	v_add_u32_e32 v26, v26, v25
	v_lshlrev_b32_e32 v26, 2, v26
	s_add_u32 s88, s98, 0
	s_addc_u32 s89, s99, 0
	global_load_dwordx4 v[28:31], v26, s[88:89]
	s_mul_i32 vcc_lo, s100, 0x2c00
	s_add_u32 s88, s96, vcc_lo
	s_addc_u32 s89, s97, 0
	s_add_u32 s88, s88, 0x11f00400
	s_addc_u32 s89, s89, 0
	s_mul_i32 vcc_lo, s101, 0x800
	s_add_u32 s92, s96, vcc_lo
	s_addc_u32 s93, s97, 0
	s_add_u32 s92, s92, 0x2100000
	s_addc_u32 s93, s93, 0
	v_lshl_add_u64 v[0:1], s[88:89], 0, v[12:13]
	v_lshl_add_u64 v[2:3], s[92:93], 0, v[14:15]
	v_mov_b32_e32 v16, 0
	v_mov_b32_e32 v17, 0
	v_mov_b32_e32 v18, 0
	v_mov_b32_e32 v19, 0
	global_load_dwordx4 v[40:43], v[0:1], off
	global_load_dwordx4 v[44:47], v[2:3], off
	global_load_dwordx4 v[48:51], v[0:1], off offset:64
	global_load_dwordx4 v[52:55], v[2:3], off offset:64
	global_load_dwordx4 v[56:59], v[0:1], off offset:128
	global_load_dwordx4 v[60:63], v[2:3], off offset:128
	global_load_dwordx4 v[64:67], v[0:1], off offset:192
	global_load_dwordx4 v[68:71], v[2:3], off offset:192
	global_load_dwordx4 v[72:75], v[0:1], off offset:256
	global_load_dwordx4 v[76:79], v[2:3], off offset:256
	global_load_dwordx4 v[80:83], v[0:1], off offset:320
	global_load_dwordx4 v[84:87], v[2:3], off offset:320
	global_load_dwordx4 v[88:91], v[0:1], off offset:384
	global_load_dwordx4 v[92:95], v[2:3], off offset:384
	global_load_dwordx4 v[96:99], v[0:1], off offset:448
	global_load_dwordx4 v[100:103], v[2:3], off offset:448
	global_load_dwordx4 v[104:107], v[0:1], off offset:512
	global_load_dwordx4 v[108:111], v[2:3], off offset:512
	global_load_dwordx4 v[112:115], v[0:1], off offset:576
	global_load_dwordx4 v[116:119], v[2:3], off offset:576
	global_load_dwordx4 v[120:123], v[0:1], off offset:640
	global_load_dwordx4 v[124:127], v[2:3], off offset:640
	global_load_dwordx4 v[128:131], v[0:1], off offset:704
	global_load_dwordx4 v[132:135], v[2:3], off offset:704
	global_load_dwordx4 v[136:139], v[0:1], off offset:768
	global_load_dwordx4 v[140:143], v[2:3], off offset:768
	global_load_dwordx4 v[144:147], v[0:1], off offset:832
	global_load_dwordx4 v[148:151], v[2:3], off offset:832
	global_load_dwordx4 v[152:155], v[0:1], off offset:896
	global_load_dwordx4 v[156:159], v[2:3], off offset:896
	global_load_dwordx4 v[160:163], v[0:1], off offset:960
	global_load_dwordx4 v[164:167], v[2:3], off offset:960
	s_waitcnt vmcnt(30)
	v_mfma_f32_16x16x32_bf16 v[16:19], v[44:47], v[40:43], v[16:19]
	s_waitcnt vmcnt(28)
	v_mfma_f32_16x16x32_bf16 v[16:19], v[52:55], v[48:51], v[16:19]
	s_waitcnt vmcnt(26)
	v_mfma_f32_16x16x32_bf16 v[16:19], v[60:63], v[56:59], v[16:19]
	s_waitcnt vmcnt(24)
	v_mfma_f32_16x16x32_bf16 v[16:19], v[68:71], v[64:67], v[16:19]
	s_waitcnt vmcnt(22)
	v_mfma_f32_16x16x32_bf16 v[16:19], v[76:79], v[72:75], v[16:19]
	s_waitcnt vmcnt(20)
	v_mfma_f32_16x16x32_bf16 v[16:19], v[84:87], v[80:83], v[16:19]
	s_waitcnt vmcnt(18)
	v_mfma_f32_16x16x32_bf16 v[16:19], v[92:95], v[88:91], v[16:19]
	s_waitcnt vmcnt(16)
	v_mfma_f32_16x16x32_bf16 v[16:19], v[100:103], v[96:99], v[16:19]
	s_waitcnt vmcnt(14)
	v_mfma_f32_16x16x32_bf16 v[16:19], v[108:111], v[104:107], v[16:19]
	s_waitcnt vmcnt(12)
	v_mfma_f32_16x16x32_bf16 v[16:19], v[116:119], v[112:115], v[16:19]
	s_waitcnt vmcnt(10)
	v_mfma_f32_16x16x32_bf16 v[16:19], v[124:127], v[120:123], v[16:19]
	s_waitcnt vmcnt(8)
	v_mfma_f32_16x16x32_bf16 v[16:19], v[132:135], v[128:131], v[16:19]
	s_waitcnt vmcnt(6)
	v_mfma_f32_16x16x32_bf16 v[16:19], v[140:143], v[136:139], v[16:19]
	s_waitcnt vmcnt(4)
	v_mfma_f32_16x16x32_bf16 v[16:19], v[148:151], v[144:147], v[16:19]
	s_waitcnt vmcnt(2)
	v_mfma_f32_16x16x32_bf16 v[16:19], v[156:159], v[152:155], v[16:19]
	s_waitcnt vmcnt(0)
	v_mfma_f32_16x16x32_bf16 v[16:19], v[164:167], v[160:163], v[16:19]
	s_nop 7
	s_nop 7
	s_lshr_b32 s101, s86, 2
	s_cmp_eq_u32 s101, 1
	s_cbranch_scc0 .Lsg_p6_nowr
	ds_write_b128 v34, v[16:19]
.Lsg_p6_nowr:
	s_waitcnt lgkmcnt(0)
	s_barrier
	s_cmp_eq_u32 s101, 0
	s_cbranch_scc0 .Lsg_p6_noepi
	ds_read_b128 v[40:43], v34
	s_waitcnt lgkmcnt(0)
	v_add_f32_e32 v16, v16, v40
	v_add_f32_e32 v17, v17, v41
	v_add_f32_e32 v18, v18, v42
	v_add_f32_e32 v19, v19, v43
	v_lshlrev_b32_e32 v27, 10, v24
	v_add_u32_e32 v27, v27, v25
	v_fma_f32 v28, v16, 1.0, v28
	v_fma_f32 v29, v17, 1.0, v29
	v_fma_f32 v30, v18, 1.0, v30
	v_fma_f32 v31, v19, 1.0, v31
	v_lshlrev_b32_e32 v26, 2, v27
	global_store_dwordx4 v26, v[28:31], s[94:95]
	v_cvt_pk_bf16_f32 v40, v28, v29
	v_cvt_pk_bf16_f32 v41, v30, v31
	v_lshlrev_b32_e32 v26, 1, v27
	s_add_u32 s92, s96, 0x9e00000
	s_addc_u32 s93, s97, 0
	global_store_dwordx2 v26, v[40:41], s[92:93]
	v_mul_f32_e32 v42, v28, v28
	v_fmac_f32_e32 v42, v29, v29
	v_fmac_f32_e32 v42, v30, v30
	v_fmac_f32_e32 v42, v31, v31
	s_nop 1
	ds_bpermute_b32 v43, v32, v42
	s_waitcnt lgkmcnt(0)
	v_add_f32_e32 v42, v42, v43
	s_nop 1
	ds_bpermute_b32 v43, v33, v42
	s_waitcnt lgkmcnt(0)
	v_add_f32_e32 v42, v42, v43
	s_nop 1
	ds_write_b32 v35, v42

.Lsg_p6_done:
	v_mov_b32_e32 v0, v206
	v_mov_b32_e32 v8, v206
	s_nop 1
	s_and_b64 vcc, exec, s[6:7]
	v_readfirstlane_b32 s12, v8
	s_cbranch_vccnz .LBB0_992
	s_lshr_b32 s10, s3, 29
	s_add_i32 s13, s2, s10
	s_and_b32 s10, s13, -8
	s_sub_i32 s14, s2, s10
	s_cmp_gt_i32 s14, 3
	s_cbranch_scc0 .LBB0_989
	s_lshl_b32 s10, s14, 7
	s_or_b32 s15, s10, 0
	s_cbranch_execz .LBB0_990
	s_branch .LBB0_991

.Lsg_p7_loop:
	s_cmp_ge_u32 s87, 0x100
	s_cbranch_scc1 .Lsg_p7_done
	s_and_b32 s100, s87, 15
	s_lshl_b32 s100, s100, 4
	s_add_u32 s100, s100, 0x10000
	v_add_u32_e32 v24, s100, v9
	s_lshr_b32 s101, s87, 4
	s_lshl_b32 s101, s101, 6
	s_lshl_b32 vcc_lo, s32, 4
	s_add_u32 s101, s101, vcc_lo
	v_lshlrev_b32_e32 v25, 2, v10
	v_add_u32_e32 v25, s101, v25
	s_add_u32 s88, s96, 0x4b00000
	s_addc_u32 s89, s97, 0
	v_lshlrev_b32_e32 v26, 6, v24
	v_lshl_add_u32 v26, v10, 4, v26
	global_load_dwordx4 v[28:31], v26, s[88:89]
	s_mul_i32 vcc_lo, s100, 0x800
	s_add_u32 s88, s96, vcc_lo
	s_addc_u32 s89, s97, 0
	s_add_u32 s88, s88, 0x9e00000
	s_addc_u32 s89, s89, 0
	s_mul_i32 vcc_lo, s101, 0x800
	s_add_u32 s92, s96, vcc_lo
	s_addc_u32 s93, s97, 0
	s_add_u32 s92, s92, 0x2300000
	s_addc_u32 s93, s93, 0
	v_lshl_add_u64 v[0:1], s[88:89], 0, v[12:13]
	v_lshl_add_u64 v[2:3], s[92:93], 0, v[14:15]
	v_mov_b32_e32 v16, 0
	v_mov_b32_e32 v17, 0
	v_mov_b32_e32 v18, 0
	v_mov_b32_e32 v19, 0
	global_load_dwordx4 v[40:43], v[0:1], off
	global_load_dwordx4 v[44:47], v[2:3], off
	global_load_dwordx4 v[48:51], v[0:1], off offset:64
	global_load_dwordx4 v[52:55], v[2:3], off offset:64
	global_load_dwordx4 v[56:59], v[0:1], off offset:128
	global_load_dwordx4 v[60:63], v[2:3], off offset:128
	global_load_dwordx4 v[64:67], v[0:1], off offset:192
	global_load_dwordx4 v[68:71], v[2:3], off offset:192
	global_load_dwordx4 v[72:75], v[0:1], off offset:256
	global_load_dwordx4 v[76:79], v[2:3], off offset:256
	global_load_dwordx4 v[80:83], v[0:1], off offset:320
	global_load_dwordx4 v[84:87], v[2:3], off offset:320
	global_load_dwordx4 v[88:91], v[0:1], off offset:384
	global_load_dwordx4 v[92:95], v[2:3], off offset:384
	global_load_dwordx4 v[96:99], v[0:1], off offset:448
	global_load_dwordx4 v[100:103], v[2:3], off offset:448
	global_load_dwordx4 v[104:107], v[0:1], off offset:512
	global_load_dwordx4 v[108:111], v[2:3], off offset:512
	global_load_dwordx4 v[112:115], v[0:1], off offset:576
	global_load_dwordx4 v[116:119], v[2:3], off offset:576
	global_load_dwordx4 v[120:123], v[0:1], off offset:640
	global_load_dwordx4 v[124:127], v[2:3], off offset:640
	global_load_dwordx4 v[128:131], v[0:1], off offset:704
	global_load_dwordx4 v[132:135], v[2:3], off offset:704
	global_load_dwordx4 v[136:139], v[0:1], off offset:768
	global_load_dwordx4 v[140:143], v[2:3], off offset:768
	global_load_dwordx4 v[144:147], v[0:1], off offset:832
	global_load_dwordx4 v[148:151], v[2:3], off offset:832
	global_load_dwordx4 v[152:155], v[0:1], off offset:896
	global_load_dwordx4 v[156:159], v[2:3], off offset:896
	global_load_dwordx4 v[160:163], v[0:1], off offset:960
	global_load_dwordx4 v[164:167], v[2:3], off offset:960
	s_waitcnt vmcnt(30)
	v_mfma_f32_16x16x32_bf16 v[16:19], v[44:47], v[40:43], v[16:19]
	s_waitcnt vmcnt(28)
	v_mfma_f32_16x16x32_bf16 v[16:19], v[52:55], v[48:51], v[16:19]
	s_waitcnt vmcnt(26)
	v_mfma_f32_16x16x32_bf16 v[16:19], v[60:63], v[56:59], v[16:19]
	s_waitcnt vmcnt(24)
	v_mfma_f32_16x16x32_bf16 v[16:19], v[68:71], v[64:67], v[16:19]
	s_waitcnt vmcnt(22)
	v_mfma_f32_16x16x32_bf16 v[16:19], v[76:79], v[72:75], v[16:19]
	s_waitcnt vmcnt(20)
	v_mfma_f32_16x16x32_bf16 v[16:19], v[84:87], v[80:83], v[16:19]
	s_waitcnt vmcnt(18)
	v_mfma_f32_16x16x32_bf16 v[16:19], v[92:95], v[88:91], v[16:19]
	s_waitcnt vmcnt(16)
	v_mfma_f32_16x16x32_bf16 v[16:19], v[100:103], v[96:99], v[16:19]
	s_waitcnt vmcnt(14)
	v_mfma_f32_16x16x32_bf16 v[16:19], v[108:111], v[104:107], v[16:19]
	s_waitcnt vmcnt(12)
	v_mfma_f32_16x16x32_bf16 v[16:19], v[116:119], v[112:115], v[16:19]
	s_waitcnt vmcnt(10)
	v_mfma_f32_16x16x32_bf16 v[16:19], v[124:127], v[120:123], v[16:19]
	s_waitcnt vmcnt(8)
	v_mfma_f32_16x16x32_bf16 v[16:19], v[132:135], v[128:131], v[16:19]
	s_waitcnt vmcnt(6)
	v_mfma_f32_16x16x32_bf16 v[16:19], v[140:143], v[136:139], v[16:19]
	s_waitcnt vmcnt(4)
	v_mfma_f32_16x16x32_bf16 v[16:19], v[148:151], v[144:147], v[16:19]
	s_waitcnt vmcnt(2)
	v_mfma_f32_16x16x32_bf16 v[16:19], v[156:159], v[152:155], v[16:19]
	s_waitcnt vmcnt(0)
	v_mfma_f32_16x16x32_bf16 v[16:19], v[164:167], v[160:163], v[16:19]
	s_nop 7
	s_nop 7
	s_lshr_b32 s101, s86, 2
	s_cmp_eq_u32 s101, 1
	s_cbranch_scc0 .Lsg_p7_nowr
	ds_write_b128 v34, v[16:19]
.Lsg_p7_nowr:
	s_waitcnt lgkmcnt(0)
	s_barrier
	s_cmp_eq_u32 s101, 0
	s_cbranch_scc0 .Lsg_p7_noepi
	ds_read_b128 v[40:43], v34
	s_waitcnt lgkmcnt(0)
	v_add_f32_e32 v16, v16, v40
	v_add_f32_e32 v17, v17, v41
	v_add_f32_e32 v18, v18, v42
	v_add_f32_e32 v19, v19, v43
	v_add_f32_e32 v28, v28, v29
	v_add_f32_e32 v30, v30, v31
	v_add_f32_e32 v28, v28, v30
	s_nop 1
	ds_bpermute_b32 v29, v32, v28
	s_waitcnt lgkmcnt(0)
	v_add_f32_e32 v28, v28, v29
	s_nop 1
	ds_bpermute_b32 v29, v33, v28
	s_waitcnt lgkmcnt(0)
	v_add_f32_e32 v28, v28, v29
	v_mov_b32_e32 v29, 0x358637bd
	s_mov_b32 s101, 0x3a800000
	v_fma_f32 v28, v28, s101, v29
	v_rsq_f32_e32 v28, v28
	s_nop 1
	v_mul_f32_e32 v28, 0x3db8aa3b, v28
	v_mul_f32_e32 v16, v16, v28
	v_mul_f32_e32 v17, v17, v28
	v_mul_f32_e32 v18, v18, v28
	v_mul_f32_e32 v19, v19, v28
	v_cvt_pk_bf16_f32 v40, v16, v17
	v_cvt_pk_bf16_f32 v41, v18, v19
	v_mov_b32_e32 v26, 0x800
	v_mul_u32_u24_e32 v26, v24, v26
	v_lshl_add_u32 v26, v25, 1, v26
	s_add_u32 s92, s96, 0x11f00000
	s_addc_u32 s93, s97, 0
	global_store_dwordx2 v26, v[40:41], s[92:93]

.Lsg_p7_done:
	v_mov_b32_e32 v0, v206
	v_mov_b32_e32 v8, v206
	s_nop 1
	s_and_b64 vcc, exec, s[6:7]
	v_readfirstlane_b32 s20, v8
	s_cbranch_vccnz .LBB0_1138
	s_lshr_b32 s10, s3, 29
	s_add_i32 s13, s2, s10
	s_and_b32 s10, s13, -8
	s_sub_i32 s14, s2, s10
	s_cmp_gt_i32 s14, 3
	s_cbranch_scc0 .LBB0_1117
	s_lshl_b32 s10, s14, 7
	s_or_b32 s12, s10, 0
	s_cbranch_execz .LBB0_1118
	s_branch .LBB0_1119

.LBB0_1264:
	s_or_b64 exec, exec, s[10:11]
	s_waitcnt lgkmcnt(0)
	v_mov_b32_e32 v0, v206
	v_mov_b32_e32 v8, v206
	s_barrier
	v_lshrrev_b32_e32 v11, 6, v206
	v_and_b32_e32 v8, 63, v206
	s_load_dwordx2 s[96:97], s[0:1], 0x118
	v_readfirstlane_b32 s86, v11
	s_load_dwordx2 s[98:99], s[0:1], 0x110
	v_and_b32_e32 v9, 15, v8
	v_lshrrev_b32_e32 v10, 4, v8
	s_and_b32 s32, s86, 3
	s_lshr_b32 s101, s86, 2
	s_load_dwordx2 s[94:95], s[0:1], 0x110
	s_mov_b32 s87, s2
	v_lshlrev_b32_e32 v11, 4, v10
	s_mul_i32 s100, s101, 0x400
	v_mov_b32_e32 v12, 0x800
	v_mul_u32_u24_e32 v12, v9, v12
	v_mov_b32_e32 v14, 0x800
	v_mul_u32_u24_e32 v14, v9, v14
	v_add_u32_e32 v12, v12, v11
	v_add_u32_e32 v14, v14, v11
	v_add_u32_e32 v12, s100, v12
	v_add_u32_e32 v14, s100, v14
	v_mov_b32_e32 v13, 0
	v_mov_b32_e32 v15, 0
	s_lshl_b32 s100, s32, 10
	s_add_u32 s100, s100, 0x20000
	v_lshlrev_b32_e32 v34, 4, v8
	v_add_u32_e32 v34, s100, v34
	s_lshl_b32 s100, s32, 8
	s_add_u32 s100, s100, 0x22000
	v_lshlrev_b32_e32 v35, 2, v8
	v_add_u32_e32 v35, s100, v35
	v_xor_b32_e32 v32, 16, v8
	v_lshlrev_b32_e32 v32, 2, v32
	v_xor_b32_e32 v33, 32, v8
	v_lshlrev_b32_e32 v33, 2, v33
	s_waitcnt lgkmcnt(0)
.Lsg_p9_loop:
	s_cmp_ge_u32 s87, 0x100
	s_cbranch_scc1 .Lsg_p9_done
	s_and_b32 s100, s87, 15
	s_lshl_b32 s100, s100, 4
	s_add_u32 s100, s100, 0x10000
	v_add_u32_e32 v24, s100, v9
	s_lshr_b32 s101, s87, 4
	s_lshl_b32 s101, s101, 6
	s_lshl_b32 vcc_lo, s32, 4
	s_add_u32 s101, s101, vcc_lo
	v_lshlrev_b32_e32 v25, 2, v10
	v_add_u32_e32 v25, s101, v25
	v_add_u32_e32 v26, 0, v24
	v_lshlrev_b32_e32 v26, 10, v26
	v_add_u32_e32 v26, v26, v25
	v_lshlrev_b32_e32 v26, 2, v26
	s_add_u32 s88, s98, 0
	s_addc_u32 s89, s99, 0
	global_load_dwordx4 v[28:31], v26, s[88:89]
	s_mul_i32 vcc_lo, s100, 0x800
	s_add_u32 s88, s96, vcc_lo
	s_addc_u32 s89, s97, 0
	s_add_u32 s88, s88, 0x1bf00000
	s_addc_u32 s89, s89, 0
	s_mul_i32 vcc_lo, s101, 0x800
	s_add_u32 s92, s96, vcc_lo
	s_addc_u32 s93, s97, 0
	s_add_u32 s92, s92, 0x2500000
	s_addc_u32 s93, s93, 0
	v_lshl_add_u64 v[0:1], s[88:89], 0, v[12:13]
	v_lshl_add_u64 v[2:3], s[92:93], 0, v[14:15]
	v_mov_b32_e32 v16, 0
	v_mov_b32_e32 v17, 0
	v_mov_b32_e32 v18, 0
	v_mov_b32_e32 v19, 0
	global_load_dwordx4 v[40:43], v[0:1], off
	global_load_dwordx4 v[44:47], v[2:3], off
	global_load_dwordx4 v[48:51], v[0:1], off offset:64
	global_load_dwordx4 v[52:55], v[2:3], off offset:64
	global_load_dwordx4 v[56:59], v[0:1], off offset:128
	global_load_dwordx4 v[60:63], v[2:3], off offset:128
	global_load_dwordx4 v[64:67], v[0:1], off offset:192
	global_load_dwordx4 v[68:71], v[2:3], off offset:192
	global_load_dwordx4 v[72:75], v[0:1], off offset:256
	global_load_dwordx4 v[76:79], v[2:3], off offset:256
	global_load_dwordx4 v[80:83], v[0:1], off offset:320
	global_load_dwordx4 v[84:87], v[2:3], off offset:320
	global_load_dwordx4 v[88:91], v[0:1], off offset:384
	global_load_dwordx4 v[92:95], v[2:3], off offset:384
	global_load_dwordx4 v[96:99], v[0:1], off offset:448
	global_load_dwordx4 v[100:103], v[2:3], off offset:448
	global_load_dwordx4 v[104:107], v[0:1], off offset:512
	global_load_dwordx4 v[108:111], v[2:3], off offset:512
	global_load_dwordx4 v[112:115], v[0:1], off offset:576
	global_load_dwordx4 v[116:119], v[2:3], off offset:576
	global_load_dwordx4 v[120:123], v[0:1], off offset:640
	global_load_dwordx4 v[124:127], v[2:3], off offset:640
	global_load_dwordx4 v[128:131], v[0:1], off offset:704
	global_load_dwordx4 v[132:135], v[2:3], off offset:704
	global_load_dwordx4 v[136:139], v[0:1], off offset:768
	global_load_dwordx4 v[140:143], v[2:3], off offset:768
	global_load_dwordx4 v[144:147], v[0:1], off offset:832
	global_load_dwordx4 v[148:151], v[2:3], off offset:832
	global_load_dwordx4 v[152:155], v[0:1], off offset:896
	global_load_dwordx4 v[156:159], v[2:3], off offset:896
	global_load_dwordx4 v[160:163], v[0:1], off offset:960
	global_load_dwordx4 v[164:167], v[2:3], off offset:960
	s_waitcnt vmcnt(30)
	v_mfma_f32_16x16x32_bf16 v[16:19], v[44:47], v[40:43], v[16:19]
	s_waitcnt vmcnt(28)
	v_mfma_f32_16x16x32_bf16 v[16:19], v[52:55], v[48:51], v[16:19]
	s_waitcnt vmcnt(26)
	v_mfma_f32_16x16x32_bf16 v[16:19], v[60:63], v[56:59], v[16:19]
	s_waitcnt vmcnt(24)
	v_mfma_f32_16x16x32_bf16 v[16:19], v[68:71], v[64:67], v[16:19]
	s_waitcnt vmcnt(22)
	v_mfma_f32_16x16x32_bf16 v[16:19], v[76:79], v[72:75], v[16:19]
	s_waitcnt vmcnt(20)
	v_mfma_f32_16x16x32_bf16 v[16:19], v[84:87], v[80:83], v[16:19]
	s_waitcnt vmcnt(18)
	v_mfma_f32_16x16x32_bf16 v[16:19], v[92:95], v[88:91], v[16:19]
	s_waitcnt vmcnt(16)
	v_mfma_f32_16x16x32_bf16 v[16:19], v[100:103], v[96:99], v[16:19]
	s_waitcnt vmcnt(14)
	v_mfma_f32_16x16x32_bf16 v[16:19], v[108:111], v[104:107], v[16:19]
	s_waitcnt vmcnt(12)
	v_mfma_f32_16x16x32_bf16 v[16:19], v[116:119], v[112:115], v[16:19]
	s_waitcnt vmcnt(10)
	v_mfma_f32_16x16x32_bf16 v[16:19], v[124:127], v[120:123], v[16:19]
	s_waitcnt vmcnt(8)
	v_mfma_f32_16x16x32_bf16 v[16:19], v[132:135], v[128:131], v[16:19]
	s_waitcnt vmcnt(6)
	v_mfma_f32_16x16x32_bf16 v[16:19], v[140:143], v[136:139], v[16:19]
	s_waitcnt vmcnt(4)
	v_mfma_f32_16x16x32_bf16 v[16:19], v[148:151], v[144:147], v[16:19]
	s_waitcnt vmcnt(2)
	v_mfma_f32_16x16x32_bf16 v[16:19], v[156:159], v[152:155], v[16:19]
	s_waitcnt vmcnt(0)
	v_mfma_f32_16x16x32_bf16 v[16:19], v[164:167], v[160:163], v[16:19]
	s_nop 7
	s_nop 7
	s_lshr_b32 s101, s86, 2
	s_cmp_eq_u32 s101, 1
	s_cbranch_scc0 .Lsg_p9_nowr
	ds_write_b128 v34, v[16:19]

.Lsg_p9_done:
	v_mov_b32_e32 v0, v206
	v_mov_b32_e32 v8, v206
	s_nop 1
	s_and_b64 vcc, exec, s[6:7]
	v_readfirstlane_b32 s12, v8
	s_cbranch_vccnz .LBB0_1270
	s_lshr_b32 s10, s3, 29
	s_add_i32 s13, s2, s10
	s_and_b32 s10, s13, -8
	s_sub_i32 s18, s2, s10
	s_cmp_gt_i32 s18, 3
	s_cbranch_scc0 .LBB0_1267
	s_lshl_b32 s10, s18, 7
	s_or_b32 s19, s10, 0
	s_cbranch_execz .LBB0_1268
	s_branch .LBB0_1269

.LBB0_1390:
	s_or_b64 exec, exec, s[10:11]
	s_waitcnt lgkmcnt(0)
	v_mov_b32_e32 v0, v206
	v_mov_b32_e32 v8, v206
	s_barrier
	v_lshrrev_b32_e32 v11, 6, v206
	v_and_b32_e32 v8, 63, v206
	s_load_dwordx2 s[96:97], s[0:1], 0x118
	v_readfirstlane_b32 s86, v11
	v_and_b32_e32 v9, 15, v8
	v_lshrrev_b32_e32 v10, 4, v8
	s_mov_b32 s32, s86
	s_mov_b32 s101, 0
	s_mov_b32 s87, s2
	v_lshlrev_b32_e32 v11, 4, v10
	s_mul_i32 s100, s101, 0x400
	v_mov_b32_e32 v12, 0x800
	v_mul_u32_u24_e32 v12, v9, v12
	v_mov_b32_e32 v14, 0x800
	v_mul_u32_u24_e32 v14, v9, v14
	v_add_u32_e32 v12, v12, v11
	v_add_u32_e32 v14, v14, v11
	v_add_u32_e32 v12, s100, v12
	v_add_u32_e32 v14, s100, v14
	v_mov_b32_e32 v13, 0
	v_mov_b32_e32 v15, 0
	s_lshl_b32 s100, s32, 10
	s_add_u32 s100, s100, 0x20000
	v_lshlrev_b32_e32 v34, 4, v8
	v_add_u32_e32 v34, s100, v34
	s_lshl_b32 s100, s32, 8
	s_add_u32 s100, s100, 0x22000
	v_lshlrev_b32_e32 v35, 2, v8
	v_add_u32_e32 v35, s100, v35
	v_xor_b32_e32 v32, 16, v8
	v_lshlrev_b32_e32 v32, 2, v32
	v_xor_b32_e32 v33, 32, v8
	v_lshlrev_b32_e32 v33, 2, v33
	s_waitcnt lgkmcnt(0)
.Lsg_p10_loop:
	s_cmp_ge_u32 s87, 0x160
	s_cbranch_scc1 .Lsg_p10_done
	s_and_b32 s100, s87, 15
	s_lshl_b32 s100, s100, 4
	s_add_u32 s100, s100, 0x10000
	v_add_u32_e32 v24, s100, v9
	s_lshr_b32 s101, s87, 4
	s_lshl_b32 s101, s101, 7
	s_lshl_b32 vcc_lo, s32, 4
	s_add_u32 s101, s101, vcc_lo
	v_lshlrev_b32_e32 v25, 2, v10
	v_add_u32_e32 v25, s101, v25
	s_add_u32 s88, s96, 0x5000000
	s_addc_u32 s89, s97, 0
	v_lshlrev_b32_e32 v26, 6, v24
	v_lshl_add_u32 v26, v10, 4, v26
	global_load_dwordx4 v[28:31], v26, s[88:89]
	s_mul_i32 vcc_lo, s100, 0x800
	s_add_u32 s88, s96, vcc_lo
	s_addc_u32 s89, s97, 0
	s_add_u32 s88, s88, 0x9e00000
	s_addc_u32 s89, s89, 0
	s_lshr_b32 vcc_lo, s101, 7
	s_lshl_b32 vcc_lo, vcc_lo, 8
	s_and_b32 vcc_hi, s101, 0x7f
	s_add_u32 vcc_lo, vcc_lo, vcc_hi
	s_mul_i32 vcc_lo, vcc_lo, 0x800
	s_add_u32 s92, s96, vcc_lo
	s_addc_u32 s93, s97, 0
	s_add_u32 s92, s92, 0x2b00000
	s_addc_u32 s93, s93, 0
	v_lshl_add_u64 v[0:1], s[88:89], 0, v[12:13]
	v_lshl_add_u64 v[2:3], s[92:93], 0, v[14:15]
	s_mov_b32 vcc_lo, 0x40000
	s_mov_b32 vcc_hi, 0
	v_lshl_add_u64 v[4:5], v[2:3], 0, vcc
	v_mov_b32_e32 v16, 0
	v_mov_b32_e32 v17, 0
	v_mov_b32_e32 v18, 0
	v_mov_b32_e32 v19, 0
	v_mov_b32_e32 v20, 0
	v_mov_b32_e32 v21, 0
	v_mov_b32_e32 v22, 0
	v_mov_b32_e32 v23, 0
	global_load_dwordx4 v[40:43], v[0:1], off
	global_load_dwordx4 v[44:47], v[2:3], off
	global_load_dwordx4 v[48:51], v[4:5], off
	global_load_dwordx4 v[52:55], v[0:1], off offset:64
	global_load_dwordx4 v[56:59], v[2:3], off offset:64
	global_load_dwordx4 v[60:63], v[4:5], off offset:64
	global_load_dwordx4 v[64:67], v[0:1], off offset:128
	global_load_dwordx4 v[68:71], v[2:3], off offset:128
	global_load_dwordx4 v[72:75], v[4:5], off offset:128
	global_load_dwordx4 v[76:79], v[0:1], off offset:192
	global_load_dwordx4 v[80:83], v[2:3], off offset:192
	global_load_dwordx4 v[84:87], v[4:5], off offset:192
	global_load_dwordx4 v[88:91], v[0:1], off offset:256
	global_load_dwordx4 v[92:95], v[2:3], off offset:256
	global_load_dwordx4 v[96:99], v[4:5], off offset:256
	global_load_dwordx4 v[100:103], v[0:1], off offset:320
	global_load_dwordx4 v[104:107], v[2:3], off offset:320
	global_load_dwordx4 v[108:111], v[4:5], off offset:320
	global_load_dwordx4 v[112:115], v[0:1], off offset:384
	global_load_dwordx4 v[116:119], v[2:3], off offset:384
	global_load_dwordx4 v[120:123], v[4:5], off offset:384
	global_load_dwordx4 v[124:127], v[0:1], off offset:448
	global_load_dwordx4 v[128:131], v[2:3], off offset:448
	global_load_dwordx4 v[132:135], v[4:5], off offset:448
	global_load_dwordx4 v[136:139], v[0:1], off offset:512
	global_load_dwordx4 v[140:143], v[2:3], off offset:512
	global_load_dwordx4 v[144:147], v[4:5], off offset:512
	global_load_dwordx4 v[148:151], v[0:1], off offset:576
	global_load_dwordx4 v[152:155], v[2:3], off offset:576
	global_load_dwordx4 v[156:159], v[4:5], off offset:576
	global_load_dwordx4 v[160:163], v[0:1], off offset:640
	global_load_dwordx4 v[164:167], v[2:3], off offset:640
	global_load_dwordx4 v[168:171], v[4:5], off offset:640
	global_load_dwordx4 v[172:175], v[0:1], off offset:704
	global_load_dwordx4 v[176:179], v[2:3], off offset:704
	global_load_dwordx4 v[180:183], v[4:5], off offset:704
	global_load_dwordx4 v[184:187], v[0:1], off offset:768
	global_load_dwordx4 v[188:191], v[2:3], off offset:768
	global_load_dwordx4 v[192:195], v[4:5], off offset:768
	global_load_dwordx4 v[196:199], v[0:1], off offset:832
	global_load_dwordx4 v[200:203], v[2:3], off offset:832
	global_load_dwordx4 v[212:215], v[4:5], off offset:832
	global_load_dwordx4 v[216:219], v[0:1], off offset:896
	global_load_dwordx4 v[220:223], v[2:3], off offset:896
	global_load_dwordx4 v[224:227], v[4:5], off offset:896
	global_load_dwordx4 v[228:231], v[0:1], off offset:960
	global_load_dwordx4 v[232:235], v[2:3], off offset:960
	global_load_dwordx4 v[236:239], v[4:5], off offset:960
	s_waitcnt vmcnt(45)
	v_mfma_f32_16x16x32_bf16 v[16:19], v[44:47], v[40:43], v[16:19]
	v_mfma_f32_16x16x32_bf16 v[20:23], v[48:51], v[40:43], v[20:23]
	s_waitcnt vmcnt(42)
	v_mfma_f32_16x16x32_bf16 v[16:19], v[56:59], v[52:55], v[16:19]
	v_mfma_f32_16x16x32_bf16 v[20:23], v[60:63], v[52:55], v[20:23]
	s_waitcnt vmcnt(39)
	v_mfma_f32_16x16x32_bf16 v[16:19], v[68:71], v[64:67], v[16:19]
	v_mfma_f32_16x16x32_bf16 v[20:23], v[72:75], v[64:67], v[20:23]
	s_waitcnt vmcnt(36)
	v_mfma_f32_16x16x32_bf16 v[16:19], v[80:83], v[76:79], v[16:19]
	v_mfma_f32_16x16x32_bf16 v[20:23], v[84:87], v[76:79], v[20:23]
	s_waitcnt vmcnt(33)
	v_mfma_f32_16x16x32_bf16 v[16:19], v[92:95], v[88:91], v[16:19]
	v_mfma_f32_16x16x32_bf16 v[20:23], v[96:99], v[88:91], v[20:23]
	s_waitcnt vmcnt(30)
	v_mfma_f32_16x16x32_bf16 v[16:19], v[104:107], v[100:103], v[16:19]
	v_mfma_f32_16x16x32_bf16 v[20:23], v[108:111], v[100:103], v[20:23]
	s_waitcnt vmcnt(27)
	v_mfma_f32_16x16x32_bf16 v[16:19], v[116:119], v[112:115], v[16:19]
	v_mfma_f32_16x16x32_bf16 v[20:23], v[120:123], v[112:115], v[20:23]
	s_waitcnt vmcnt(24)
	v_mfma_f32_16x16x32_bf16 v[16:19], v[128:131], v[124:127], v[16:19]
	v_mfma_f32_16x16x32_bf16 v[20:23], v[132:135], v[124:127], v[20:23]
	global_load_dwordx4 v[40:43], v[0:1], off offset:1024
	global_load_dwordx4 v[44:47], v[2:3], off offset:1024
	global_load_dwordx4 v[48:51], v[4:5], off offset:1024
	global_load_dwordx4 v[52:55], v[0:1], off offset:1088
	global_load_dwordx4 v[56:59], v[2:3], off offset:1088
	global_load_dwordx4 v[60:63], v[4:5], off offset:1088
	global_load_dwordx4 v[64:67], v[0:1], off offset:1152
	global_load_dwordx4 v[68:71], v[2:3], off offset:1152
	global_load_dwordx4 v[72:75], v[4:5], off offset:1152
	global_load_dwordx4 v[76:79], v[0:1], off offset:1216
	global_load_dwordx4 v[80:83], v[2:3], off offset:1216
	global_load_dwordx4 v[84:87], v[4:5], off offset:1216
	global_load_dwordx4 v[88:91], v[0:1], off offset:1280
	global_load_dwordx4 v[92:95], v[2:3], off offset:1280
	global_load_dwordx4 v[96:99], v[4:5], off offset:1280
	global_load_dwordx4 v[100:103], v[0:1], off offset:1344
	global_load_dwordx4 v[104:107], v[2:3], off offset:1344
	global_load_dwordx4 v[108:111], v[4:5], off offset:1344
	global_load_dwordx4 v[112:115], v[0:1], off offset:1408
	global_load_dwordx4 v[116:119], v[2:3], off offset:1408
	global_load_dwordx4 v[120:123], v[4:5], off offset:1408
	global_load_dwordx4 v[124:127], v[0:1], off offset:1472
	global_load_dwordx4 v[128:131], v[2:3], off offset:1472
	global_load_dwordx4 v[132:135], v[4:5], off offset:1472
	s_waitcnt vmcnt(45)
	v_mfma_f32_16x16x32_bf16 v[16:19], v[140:143], v[136:139], v[16:19]
	v_mfma_f32_16x16x32_bf16 v[20:23], v[144:147], v[136:139], v[20:23]
	s_waitcnt vmcnt(42)
	v_mfma_f32_16x16x32_bf16 v[16:19], v[152:155], v[148:151], v[16:19]
	v_mfma_f32_16x16x32_bf16 v[20:23], v[156:159], v[148:151], v[20:23]
	s_waitcnt vmcnt(39)
	v_mfma_f32_16x16x32_bf16 v[16:19], v[164:167], v[160:163], v[16:19]
	v_mfma_f32_16x16x32_bf16 v[20:23], v[168:171], v[160:163], v[20:23]
	s_waitcnt vmcnt(36)
	v_mfma_f32_16x16x32_bf16 v[16:19], v[176:179], v[172:175], v[16:19]
	v_mfma_f32_16x16x32_bf16 v[20:23], v[180:183], v[172:175], v[20:23]
	s_waitcnt vmcnt(33)
	v_mfma_f32_16x16x32_bf16 v[16:19], v[188:191], v[184:187], v[16:19]
	v_mfma_f32_16x16x32_bf16 v[20:23], v[192:195], v[184:187], v[20:23]
	s_waitcnt vmcnt(30)
	v_mfma_f32_16x16x32_bf16 v[16:19], v[200:203], v[196:199], v[16:19]
	v_mfma_f32_16x16x32_bf16 v[20:23], v[212:215], v[196:199], v[20:23]
	s_waitcnt vmcnt(27)
	v_mfma_f32_16x16x32_bf16 v[16:19], v[220:223], v[216:219], v[16:19]
	v_mfma_f32_16x16x32_bf16 v[20:23], v[224:227], v[216:219], v[20:23]
	s_waitcnt vmcnt(24)
	v_mfma_f32_16x16x32_bf16 v[16:19], v[232:235], v[228:231], v[16:19]
	v_mfma_f32_16x16x32_bf16 v[20:23], v[236:239], v[228:231], v[20:23]
	global_load_dwordx4 v[136:139], v[0:1], off offset:1536
	global_load_dwordx4 v[140:143], v[2:3], off offset:1536
	global_load_dwordx4 v[144:147], v[4:5], off offset:1536
	global_load_dwordx4 v[148:151], v[0:1], off offset:1600
	global_load_dwordx4 v[152:155], v[2:3], off offset:1600
	global_load_dwordx4 v[156:159], v[4:5], off offset:1600
	global_load_dwordx4 v[160:163], v[0:1], off offset:1664
	global_load_dwordx4 v[164:167], v[2:3], off offset:1664
	global_load_dwordx4 v[168:171], v[4:5], off offset:1664
	global_load_dwordx4 v[172:175], v[0:1], off offset:1728
	global_load_dwordx4 v[176:179], v[2:3], off offset:1728
	global_load_dwordx4 v[180:183], v[4:5], off offset:1728
	global_load_dwordx4 v[184:187], v[0:1], off offset:1792
	global_load_dwordx4 v[188:191], v[2:3], off offset:1792
	global_load_dwordx4 v[192:195], v[4:5], off offset:1792
	global_load_dwordx4 v[196:199], v[0:1], off offset:1856
	global_load_dwordx4 v[200:203], v[2:3], off offset:1856
	global_load_dwordx4 v[212:215], v[4:5], off offset:1856
	global_load_dwordx4 v[216:219], v[0:1], off offset:1920
	global_load_dwordx4 v[220:223], v[2:3], off offset:1920
	global_load_dwordx4 v[224:227], v[4:5], off offset:1920
	global_load_dwordx4 v[228:231], v[0:1], off offset:1984
	global_load_dwordx4 v[232:235], v[2:3], off offset:1984
	global_load_dwordx4 v[236:239], v[4:5], off offset:1984
	s_waitcnt vmcnt(45)
	v_mfma_f32_16x16x32_bf16 v[16:19], v[44:47], v[40:43], v[16:19]
	v_mfma_f32_16x16x32_bf16 v[20:23], v[48:51], v[40:43], v[20:23]
	s_waitcnt vmcnt(42)
	v_mfma_f32_16x16x32_bf16 v[16:19], v[56:59], v[52:55], v[16:19]
	v_mfma_f32_16x16x32_bf16 v[20:23], v[60:63], v[52:55], v[20:23]
	s_waitcnt vmcnt(39)
	v_mfma_f32_16x16x32_bf16 v[16:19], v[68:71], v[64:67], v[16:19]
	v_mfma_f32_16x16x32_bf16 v[20:23], v[72:75], v[64:67], v[20:23]
	s_waitcnt vmcnt(36)
	v_mfma_f32_16x16x32_bf16 v[16:19], v[80:83], v[76:79], v[16:19]
	v_mfma_f32_16x16x32_bf16 v[20:23], v[84:87], v[76:79], v[20:23]
	s_waitcnt vmcnt(33)
	v_mfma_f32_16x16x32_bf16 v[16:19], v[92:95], v[88:91], v[16:19]
	v_mfma_f32_16x16x32_bf16 v[20:23], v[96:99], v[88:91], v[20:23]
	s_waitcnt vmcnt(30)
	v_mfma_f32_16x16x32_bf16 v[16:19], v[104:107], v[100:103], v[16:19]
	v_mfma_f32_16x16x32_bf16 v[20:23], v[108:111], v[100:103], v[20:23]
	s_waitcnt vmcnt(27)
	v_mfma_f32_16x16x32_bf16 v[16:19], v[116:119], v[112:115], v[16:19]
	v_mfma_f32_16x16x32_bf16 v[20:23], v[120:123], v[112:115], v[20:23]
	s_waitcnt vmcnt(24)
	v_mfma_f32_16x16x32_bf16 v[16:19], v[128:131], v[124:127], v[16:19]
	v_mfma_f32_16x16x32_bf16 v[20:23], v[132:135], v[124:127], v[20:23]
	s_waitcnt vmcnt(21)
	v_mfma_f32_16x16x32_bf16 v[16:19], v[140:143], v[136:139], v[16:19]
	v_mfma_f32_16x16x32_bf16 v[20:23], v[144:147], v[136:139], v[20:23]
	s_waitcnt vmcnt(18)
	v_mfma_f32_16x16x32_bf16 v[16:19], v[152:155], v[148:151], v[16:19]
	v_mfma_f32_16x16x32_bf16 v[20:23], v[156:159], v[148:151], v[20:23]
	s_waitcnt vmcnt(15)
	v_mfma_f32_16x16x32_bf16 v[16:19], v[164:167], v[160:163], v[16:19]
	v_mfma_f32_16x16x32_bf16 v[20:23], v[168:171], v[160:163], v[20:23]
	s_waitcnt vmcnt(12)
	v_mfma_f32_16x16x32_bf16 v[16:19], v[176:179], v[172:175], v[16:19]
	v_mfma_f32_16x16x32_bf16 v[20:23], v[180:183], v[172:175], v[20:23]
	s_waitcnt vmcnt(9)
	v_mfma_f32_16x16x32_bf16 v[16:19], v[188:191], v[184:187], v[16:19]
	v_mfma_f32_16x16x32_bf16 v[20:23], v[192:195], v[184:187], v[20:23]
	s_waitcnt vmcnt(6)
	v_mfma_f32_16x16x32_bf16 v[16:19], v[200:203], v[196:199], v[16:19]
	v_mfma_f32_16x16x32_bf16 v[20:23], v[212:215], v[196:199], v[20:23]
	s_waitcnt vmcnt(3)
	v_mfma_f32_16x16x32_bf16 v[16:19], v[220:223], v[216:219], v[16:19]
	v_mfma_f32_16x16x32_bf16 v[20:23], v[224:227], v[216:219], v[20:23]
	s_waitcnt vmcnt(0)
	v_mfma_f32_16x16x32_bf16 v[16:19], v[232:235], v[228:231], v[16:19]
	v_mfma_f32_16x16x32_bf16 v[20:23], v[236:239], v[228:231], v[20:23]
	s_nop 7
	s_nop 7
	v_add_f32_e32 v28, v28, v29
	v_add_f32_e32 v30, v30, v31
	v_add_f32_e32 v28, v28, v30
	s_nop 1
	ds_bpermute_b32 v29, v32, v28
	s_waitcnt lgkmcnt(0)
	v_add_f32_e32 v28, v28, v29
	s_nop 1
	ds_bpermute_b32 v29, v33, v28
	s_waitcnt lgkmcnt(0)
	v_add_f32_e32 v28, v28, v29
	v_mov_b32_e32 v29, 0x358637bd
	s_mov_b32 s101, 0x3a800000
	v_fma_f32 v28, v28, s101, v29
	v_rsq_f32_e32 v28, v28
	s_nop 1
	v_mul_f32_e32 v16, v16, v28
	v_mul_f32_e32 v20, v20, v28
	v_mul_f32_e32 v17, v17, v28
	v_mul_f32_e32 v21, v21, v28
	v_mul_f32_e32 v18, v18, v28
	v_mul_f32_e32 v22, v22, v28
	v_mul_f32_e32 v19, v19, v28
	v_mul_f32_e32 v23, v23, v28
	v_mul_f32_e32 v44, 0xbfb8aa3b, v16
	v_mul_f32_e32 v45, 0xbfb8aa3b, v17
	v_mul_f32_e32 v46, 0xbfb8aa3b, v18
	v_mul_f32_e32 v47, 0xbfb8aa3b, v19
	v_exp_f32_e32 v44, v44
	v_exp_f32_e32 v45, v45
	v_exp_f32_e32 v46, v46
	v_exp_f32_e32 v47, v47
	s_nop 1
	v_add_f32_e32 v44, 1.0, v44
	v_add_f32_e32 v45, 1.0, v45
	v_add_f32_e32 v46, 1.0, v46
	v_add_f32_e32 v47, 1.0, v47
	v_rcp_f32_e32 v44, v44
	v_rcp_f32_e32 v45, v45
	v_rcp_f32_e32 v46, v46
	v_rcp_f32_e32 v47, v47
	s_nop 1
	v_mul_f32_e32 v44, v16, v44
	v_mul_f32_e32 v44, v44, v20
	v_mul_f32_e32 v45, v17, v45
	v_mul_f32_e32 v45, v45, v21
	v_mul_f32_e32 v46, v18, v46
	v_mul_f32_e32 v46, v46, v22
	v_mul_f32_e32 v47, v19, v47
	v_mul_f32_e32 v47, v47, v23
	v_cvt_pk_bf16_f32 v40, v44, v45
	v_cvt_pk_bf16_f32 v41, v46, v47
	v_mov_b32_e32 v26, 0x1600
	v_mul_u32_u24_e32 v26, v24, v26
	v_lshl_add_u32 v26, v25, 1, v26
	s_add_u32 s92, s96, 0x11f00000
	s_addc_u32 s93, s97, 0
	global_store_dwordx2 v26, v[40:41], s[92:93]

.Lsg_p10_done:
	v_mov_b32_e32 v0, v206
	v_mov_b32_e32 v8, v206
	s_nop 1
	s_and_b64 vcc, exec, s[8:9]
	v_readfirstlane_b32 s14, v8
	s_cbranch_vccnz .LBB0_1414
	s_lshr_b32 s8, s3, 29
	s_add_i32 s11, s2, s8
	s_and_b32 s8, s11, -8
	s_sub_i32 s12, s2, s8
	s_cmp_gt_i32 s12, 5
	s_cbranch_scc0 .LBB0_1393
	s_mul_i32 s8, s12, 0x2c0
	s_add_i32 s10, s8, 0
	s_cbranch_execz .LBB0_1394
	s_branch .LBB0_1395

.LBB0_1466:
	s_or_b64 exec, exec, s[8:9]
	s_waitcnt lgkmcnt(0)
	v_mov_b32_e32 v0, v206
	v_mov_b32_e32 v8, v206
	s_barrier
	v_lshrrev_b32_e32 v11, 6, v206
	v_and_b32_e32 v8, 63, v206
	s_load_dwordx2 s[96:97], s[0:1], 0x118
	v_readfirstlane_b32 s86, v11
	s_load_dwordx2 s[98:99], s[0:1], 0x110
	v_and_b32_e32 v9, 15, v8
	v_lshrrev_b32_e32 v10, 4, v8
	s_and_b32 s32, s86, 3
	s_lshr_b32 s101, s86, 2
	s_load_dwordx2 s[94:95], s[0:1], 0x110
	s_mov_b32 s87, s2
	v_lshlrev_b32_e32 v11, 4, v10
	s_mul_i32 s100, s101, 0xb00
	v_mov_b32_e32 v12, 0x1600
	v_mul_u32_u24_e32 v12, v9, v12
	v_mov_b32_e32 v14, 0x1600
	v_mul_u32_u24_e32 v14, v9, v14
	v_add_u32_e32 v12, v12, v11
	v_add_u32_e32 v14, v14, v11
	v_add_u32_e32 v12, s100, v12
	v_add_u32_e32 v14, s100, v14
	v_mov_b32_e32 v13, 0
	v_mov_b32_e32 v15, 0
	s_lshl_b32 s100, s32, 10
	s_add_u32 s100, s100, 0x20000
	v_lshlrev_b32_e32 v34, 4, v8
	v_add_u32_e32 v34, s100, v34
	s_lshl_b32 s100, s32, 8
	s_add_u32 s100, s100, 0x22000
	v_lshlrev_b32_e32 v35, 2, v8
	v_add_u32_e32 v35, s100, v35
	v_xor_b32_e32 v32, 16, v8
	v_lshlrev_b32_e32 v32, 2, v32
	v_xor_b32_e32 v33, 32, v8
	v_lshlrev_b32_e32 v33, 2, v33
	s_waitcnt lgkmcnt(0)
.Lsg_p11_loop:
	s_cmp_ge_u32 s87, 0x100
	s_cbranch_scc1 .Lsg_p11_done
	s_and_b32 s100, s87, 15
	s_lshl_b32 s100, s100, 4
	s_add_u32 s100, s100, 0x10000
	v_add_u32_e32 v24, s100, v9
	s_lshr_b32 s101, s87, 4
	s_lshl_b32 s101, s101, 6
	s_lshl_b32 vcc_lo, s32, 4
	s_add_u32 s101, s101, vcc_lo
	v_lshlrev_b32_e32 v25, 2, v10
	v_add_u32_e32 v25, s101, v25
	v_add_u32_e32 v26, 0, v24
	v_lshlrev_b32_e32 v26, 10, v26
	v_add_u32_e32 v26, v26, v25
	v_lshlrev_b32_e32 v26, 2, v26
	s_add_u32 s88, s98, 0
	s_addc_u32 s89, s99, 0
	global_load_dwordx4 v[28:31], v26, s[88:89]
	s_mul_i32 vcc_lo, s100, 0x1600
	s_add_u32 s88, s96, vcc_lo
	s_addc_u32 s89, s97, 0
	s_add_u32 s88, s88, 0x11f00000
	s_addc_u32 s89, s89, 0
	s_mul_i32 vcc_lo, s101, 0x1600
	s_add_u32 s92, s96, vcc_lo
	s_addc_u32 s93, s97, 0
	s_add_u32 s92, s92, 0x3700000
	s_addc_u32 s93, s93, 0
	v_lshl_add_u64 v[0:1], s[88:89], 0, v[12:13]
	v_lshl_add_u64 v[2:3], s[92:93], 0, v[14:15]
	v_mov_b32_e32 v16, 0
	v_mov_b32_e32 v17, 0
	v_mov_b32_e32 v18, 0
	v_mov_b32_e32 v19, 0
	global_load_dwordx4 v[40:43], v[0:1], off
	global_load_dwordx4 v[44:47], v[2:3], off
	global_load_dwordx4 v[48:51], v[0:1], off offset:64
	global_load_dwordx4 v[52:55], v[2:3], off offset:64
	global_load_dwordx4 v[56:59], v[0:1], off offset:128
	global_load_dwordx4 v[60:63], v[2:3], off offset:128
	global_load_dwordx4 v[64:67], v[0:1], off offset:192
	global_load_dwordx4 v[68:71], v[2:3], off offset:192
	global_load_dwordx4 v[72:75], v[0:1], off offset:256
	global_load_dwordx4 v[76:79], v[2:3], off offset:256
	global_load_dwordx4 v[80:83], v[0:1], off offset:320
	global_load_dwordx4 v[84:87], v[2:3], off offset:320
	global_load_dwordx4 v[88:91], v[0:1], off offset:384
	global_load_dwordx4 v[92:95], v[2:3], off offset:384
	global_load_dwordx4 v[96:99], v[0:1], off offset:448
	global_load_dwordx4 v[100:103], v[2:3], off offset:448
	global_load_dwordx4 v[104:107], v[0:1], off offset:512
	global_load_dwordx4 v[108:111], v[2:3], off offset:512
	global_load_dwordx4 v[112:115], v[0:1], off offset:576
	global_load_dwordx4 v[116:119], v[2:3], off offset:576
	global_load_dwordx4 v[120:123], v[0:1], off offset:640
	global_load_dwordx4 v[124:127], v[2:3], off offset:640
	global_load_dwordx4 v[128:131], v[0:1], off offset:704
	global_load_dwordx4 v[132:135], v[2:3], off offset:704
	global_load_dwordx4 v[136:139], v[0:1], off offset:768
	global_load_dwordx4 v[140:143], v[2:3], off offset:768
	global_load_dwordx4 v[144:147], v[0:1], off offset:832
	global_load_dwordx4 v[148:151], v[2:3], off offset:832
	global_load_dwordx4 v[152:155], v[0:1], off offset:896
	global_load_dwordx4 v[156:159], v[2:3], off offset:896
	global_load_dwordx4 v[160:163], v[0:1], off offset:960
	global_load_dwordx4 v[164:167], v[2:3], off offset:960
	global_load_dwordx4 v[168:171], v[0:1], off offset:1024
	global_load_dwordx4 v[172:175], v[2:3], off offset:1024
	global_load_dwordx4 v[176:179], v[0:1], off offset:1088
	global_load_dwordx4 v[180:183], v[2:3], off offset:1088
	global_load_dwordx4 v[184:187], v[0:1], off offset:1152
	global_load_dwordx4 v[188:191], v[2:3], off offset:1152
	global_load_dwordx4 v[192:195], v[0:1], off offset:1216
	global_load_dwordx4 v[196:199], v[2:3], off offset:1216
	global_load_dwordx4 v[200:203], v[0:1], off offset:1280
	global_load_dwordx4 v[212:215], v[2:3], off offset:1280
	global_load_dwordx4 v[216:219], v[0:1], off offset:1344
	global_load_dwordx4 v[220:223], v[2:3], off offset:1344
	s_waitcnt vmcnt(42)
	v_mfma_f32_16x16x32_bf16 v[16:19], v[44:47], v[40:43], v[16:19]
	s_waitcnt vmcnt(40)
	v_mfma_f32_16x16x32_bf16 v[16:19], v[52:55], v[48:51], v[16:19]
	s_waitcnt vmcnt(38)
	v_mfma_f32_16x16x32_bf16 v[16:19], v[60:63], v[56:59], v[16:19]
	s_waitcnt vmcnt(36)
	v_mfma_f32_16x16x32_bf16 v[16:19], v[68:71], v[64:67], v[16:19]
	s_waitcnt vmcnt(34)
	v_mfma_f32_16x16x32_bf16 v[16:19], v[76:79], v[72:75], v[16:19]
	s_waitcnt vmcnt(32)
	v_mfma_f32_16x16x32_bf16 v[16:19], v[84:87], v[80:83], v[16:19]
	s_waitcnt vmcnt(30)
	v_mfma_f32_16x16x32_bf16 v[16:19], v[92:95], v[88:91], v[16:19]
	s_waitcnt vmcnt(28)
	v_mfma_f32_16x16x32_bf16 v[16:19], v[100:103], v[96:99], v[16:19]
	s_waitcnt vmcnt(26)
	v_mfma_f32_16x16x32_bf16 v[16:19], v[108:111], v[104:107], v[16:19]
	s_waitcnt vmcnt(24)
	v_mfma_f32_16x16x32_bf16 v[16:19], v[116:119], v[112:115], v[16:19]
	s_waitcnt vmcnt(22)
	v_mfma_f32_16x16x32_bf16 v[16:19], v[124:127], v[120:123], v[16:19]
	global_load_dwordx4 v[40:43], v[0:1], off offset:1408
	global_load_dwordx4 v[44:47], v[2:3], off offset:1408
	global_load_dwordx4 v[48:51], v[0:1], off offset:1472
	global_load_dwordx4 v[52:55], v[2:3], off offset:1472
	global_load_dwordx4 v[56:59], v[0:1], off offset:1536
	global_load_dwordx4 v[60:63], v[2:3], off offset:1536
	global_load_dwordx4 v[64:67], v[0:1], off offset:1600
	global_load_dwordx4 v[68:71], v[2:3], off offset:1600
	global_load_dwordx4 v[72:75], v[0:1], off offset:1664
	global_load_dwordx4 v[76:79], v[2:3], off offset:1664
	global_load_dwordx4 v[80:83], v[0:1], off offset:1728
	global_load_dwordx4 v[84:87], v[2:3], off offset:1728
	global_load_dwordx4 v[88:91], v[0:1], off offset:1792
	global_load_dwordx4 v[92:95], v[2:3], off offset:1792
	global_load_dwordx4 v[96:99], v[0:1], off offset:1856
	global_load_dwordx4 v[100:103], v[2:3], off offset:1856
	global_load_dwordx4 v[104:107], v[0:1], off offset:1920
	global_load_dwordx4 v[108:111], v[2:3], off offset:1920
	global_load_dwordx4 v[112:115], v[0:1], off offset:1984
	global_load_dwordx4 v[116:119], v[2:3], off offset:1984
	global_load_dwordx4 v[120:123], v[0:1], off offset:2048
	global_load_dwordx4 v[124:127], v[2:3], off offset:2048
	s_waitcnt vmcnt(42)
	v_mfma_f32_16x16x32_bf16 v[16:19], v[132:135], v[128:131], v[16:19]
	s_waitcnt vmcnt(40)
	v_mfma_f32_16x16x32_bf16 v[16:19], v[140:143], v[136:139], v[16:19]
	s_waitcnt vmcnt(38)
	v_mfma_f32_16x16x32_bf16 v[16:19], v[148:151], v[144:147], v[16:19]
	s_waitcnt vmcnt(36)
	v_mfma_f32_16x16x32_bf16 v[16:19], v[156:159], v[152:155], v[16:19]
	s_waitcnt vmcnt(34)
	v_mfma_f32_16x16x32_bf16 v[16:19], v[164:167], v[160:163], v[16:19]
	s_waitcnt vmcnt(32)
	v_mfma_f32_16x16x32_bf16 v[16:19], v[172:175], v[168:171], v[16:19]
	s_waitcnt vmcnt(30)
	v_mfma_f32_16x16x32_bf16 v[16:19], v[180:183], v[176:179], v[16:19]
	s_waitcnt vmcnt(28)
	v_mfma_f32_16x16x32_bf16 v[16:19], v[188:191], v[184:187], v[16:19]
	s_waitcnt vmcnt(26)
	v_mfma_f32_16x16x32_bf16 v[16:19], v[196:199], v[192:195], v[16:19]
	s_waitcnt vmcnt(24)
	v_mfma_f32_16x16x32_bf16 v[16:19], v[212:215], v[200:203], v[16:19]
	s_waitcnt vmcnt(22)
	v_mfma_f32_16x16x32_bf16 v[16:19], v[220:223], v[216:219], v[16:19]
	global_load_dwordx4 v[128:131], v[0:1], off offset:2112
	global_load_dwordx4 v[132:135], v[2:3], off offset:2112
	global_load_dwordx4 v[136:139], v[0:1], off offset:2176
	global_load_dwordx4 v[140:143], v[2:3], off offset:2176
	global_load_dwordx4 v[144:147], v[0:1], off offset:2240
	global_load_dwordx4 v[148:151], v[2:3], off offset:2240
	global_load_dwordx4 v[152:155], v[0:1], off offset:2304
	global_load_dwordx4 v[156:159], v[2:3], off offset:2304
	global_load_dwordx4 v[160:163], v[0:1], off offset:2368
	global_load_dwordx4 v[164:167], v[2:3], off offset:2368
	global_load_dwordx4 v[168:171], v[0:1], off offset:2432
	global_load_dwordx4 v[172:175], v[2:3], off offset:2432
	global_load_dwordx4 v[176:179], v[0:1], off offset:2496
	global_load_dwordx4 v[180:183], v[2:3], off offset:2496
	global_load_dwordx4 v[184:187], v[0:1], off offset:2560
	global_load_dwordx4 v[188:191], v[2:3], off offset:2560
	global_load_dwordx4 v[192:195], v[0:1], off offset:2624
	global_load_dwordx4 v[196:199], v[2:3], off offset:2624
	global_load_dwordx4 v[200:203], v[0:1], off offset:2688
	global_load_dwordx4 v[212:215], v[2:3], off offset:2688
	global_load_dwordx4 v[216:219], v[0:1], off offset:2752
	global_load_dwordx4 v[220:223], v[2:3], off offset:2752
	s_waitcnt vmcnt(42)
	v_mfma_f32_16x16x32_bf16 v[16:19], v[44:47], v[40:43], v[16:19]
	s_waitcnt vmcnt(40)
	v_mfma_f32_16x16x32_bf16 v[16:19], v[52:55], v[48:51], v[16:19]
	s_waitcnt vmcnt(38)
	v_mfma_f32_16x16x32_bf16 v[16:19], v[60:63], v[56:59], v[16:19]
	s_waitcnt vmcnt(36)
	v_mfma_f32_16x16x32_bf16 v[16:19], v[68:71], v[64:67], v[16:19]
	s_waitcnt vmcnt(34)
	v_mfma_f32_16x16x32_bf16 v[16:19], v[76:79], v[72:75], v[16:19]
	s_waitcnt vmcnt(32)
	v_mfma_f32_16x16x32_bf16 v[16:19], v[84:87], v[80:83], v[16:19]
	s_waitcnt vmcnt(30)
	v_mfma_f32_16x16x32_bf16 v[16:19], v[92:95], v[88:91], v[16:19]
	s_waitcnt vmcnt(28)
	v_mfma_f32_16x16x32_bf16 v[16:19], v[100:103], v[96:99], v[16:19]
	s_waitcnt vmcnt(26)
	v_mfma_f32_16x16x32_bf16 v[16:19], v[108:111], v[104:107], v[16:19]
	s_waitcnt vmcnt(24)
	v_mfma_f32_16x16x32_bf16 v[16:19], v[116:119], v[112:115], v[16:19]
	s_waitcnt vmcnt(22)
	v_mfma_f32_16x16x32_bf16 v[16:19], v[124:127], v[120:123], v[16:19]
	s_waitcnt vmcnt(20)
	v_mfma_f32_16x16x32_bf16 v[16:19], v[132:135], v[128:131], v[16:19]
	s_waitcnt vmcnt(18)
	v_mfma_f32_16x16x32_bf16 v[16:19], v[140:143], v[136:139], v[16:19]
	s_waitcnt vmcnt(16)
	v_mfma_f32_16x16x32_bf16 v[16:19], v[148:151], v[144:147], v[16:19]
	s_waitcnt vmcnt(14)
	v_mfma_f32_16x16x32_bf16 v[16:19], v[156:159], v[152:155], v[16:19]
	s_waitcnt vmcnt(12)
	v_mfma_f32_16x16x32_bf16 v[16:19], v[164:167], v[160:163], v[16:19]
	s_waitcnt vmcnt(10)
	v_mfma_f32_16x16x32_bf16 v[16:19], v[172:175], v[168:171], v[16:19]
	s_waitcnt vmcnt(8)
	v_mfma_f32_16x16x32_bf16 v[16:19], v[180:183], v[176:179], v[16:19]
	s_waitcnt vmcnt(6)
	v_mfma_f32_16x16x32_bf16 v[16:19], v[188:191], v[184:187], v[16:19]
	s_waitcnt vmcnt(4)
	v_mfma_f32_16x16x32_bf16 v[16:19], v[196:199], v[192:195], v[16:19]
	s_waitcnt vmcnt(2)
	v_mfma_f32_16x16x32_bf16 v[16:19], v[212:215], v[200:203], v[16:19]
	s_waitcnt vmcnt(0)
	v_mfma_f32_16x16x32_bf16 v[16:19], v[220:223], v[216:219], v[16:19]
	s_nop 7
	s_nop 7
	s_lshr_b32 s101, s86, 2
	s_cmp_eq_u32 s101, 1
	s_cbranch_scc0 .Lsg_p11_nowr
	ds_write_b128 v34, v[16:19]
.Lsg_p11_nowr:
	s_waitcnt lgkmcnt(0)
	s_barrier
	s_cmp_eq_u32 s101, 0
	s_cbranch_scc0 .Lsg_p11_noepi
	ds_read_b128 v[40:43], v34
	s_waitcnt lgkmcnt(0)
	v_add_f32_e32 v16, v16, v40
	v_add_f32_e32 v17, v17, v41
	v_add_f32_e32 v18, v18, v42
	v_add_f32_e32 v19, v19, v43
	v_lshlrev_b32_e32 v27, 10, v24
	v_add_u32_e32 v27, v27, v25
	v_fma_f32 v28, v16, 0.5, v28
	v_fma_f32 v29, v17, 0.5, v29
	v_fma_f32 v30, v18, 0.5, v30
	v_fma_f32 v31, v19, 0.5, v31
	v_lshlrev_b32_e32 v26, 2, v27
	global_store_dwordx4 v26, v[28:31], s[94:95]
	v_mul_f32_e32 v42, v28, v28
	v_fmac_f32_e32 v42, v29, v29
	v_fmac_f32_e32 v42, v30, v30
	v_fmac_f32_e32 v42, v31, v31
	s_nop 1
	ds_bpermute_b32 v43, v32, v42
	s_waitcnt lgkmcnt(0)
	v_add_f32_e32 v42, v42, v43
	s_nop 1
	ds_bpermute_b32 v43, v33, v42
	s_waitcnt lgkmcnt(0)
	v_add_f32_e32 v42, v42, v43
	s_nop 1
	ds_write_b32 v35, v42

.Lsg_p11_done:
	v_mov_b32_e32 v0, v206
	v_mov_b32_e32 v8, v206
	s_nop 1
	s_and_b64 vcc, exec, s[6:7]
	v_readfirstlane_b32 s10, v8
	s_cbranch_vccnz .LBB0_1472
	s_lshr_b32 s8, s3, 29
	s_add_i32 s12, s2, s8
	s_and_b32 s8, s12, -8
	s_sub_i32 s11, s2, s8
	s_cmp_gt_i32 s11, 3
	s_cbranch_scc0 .LBB0_1469
	s_lshl_b32 s8, s11, 7
	s_or_b32 s13, s8, 0
	s_ashr_i32 s8, s12, 3
	s_cbranch_execz .LBB0_1470
	s_branch .LBB0_1471
